# strategy 7: LDS-DMA m0 values computed directly from the wave base with literals, address VALU used as the m0 wait state (temporaries and s_nops removed)
# speedup vs baseline: 1.0007x; 1.0007x over previous
.Lmid1_446:
	s_add_u32 s20, s56, 0xfff50080
	s_addc_u32 s21, s57, -1
	s_cmp_eq_u32 s84, 40
	s_cselect_b32 s61, s49, s21
	s_cselect_b32 s60, s48, s20
	s_cselect_b32 s21, s51, s63
	s_cselect_b32 s20, s50, s62
	s_add_i32 m0, s47, 0xc000
	v_lshl_add_u64 v[162:163], s[56:57], 0, v[156:157]
	global_load_lds_dwordx4 v[162:163], off
	s_add_i32 m0, s47, 0xe000
	v_lshl_add_u64 v[162:163], v[162:163], 0, s[2:3]
	global_load_lds_dwordx4 v[162:163], off
	s_waitcnt vmcnt(8) lgkmcnt(0)
	s_barrier
	v_mfma_f32_16x16x32_bf16 v[142:145], v[114:117], v[186:189], 0
	v_mfma_f32_16x16x32_bf16 v[142:145], v[126:129], v[194:197], v[142:145]
	v_mfma_f32_16x16x32_bf16 v[138:141], v[130:133], v[186:189], 0
	v_mfma_f32_16x16x32_bf16 v[138:141], v[134:137], v[194:197], v[138:141]
	v_mfma_f32_16x16x32_bf16 v[110:113], v[114:117], v[198:201], 0
	v_mfma_f32_16x16x32_bf16 v[110:113], v[126:129], v[214:217], v[110:113]
	v_mfma_f32_16x16x32_bf16 v[106:109], v[130:133], v[198:201], 0
	v_mfma_f32_16x16x32_bf16 v[106:109], v[134:137], v[214:217], v[106:109]
	v_mfma_f32_16x16x32_bf16 v[94:97], v[114:117], v[218:221], 0
	v_mfma_f32_16x16x32_bf16 v[94:97], v[126:129], v[222:225], v[94:97]
	v_mfma_f32_16x16x32_bf16 v[90:93], v[130:133], v[218:221], 0
	v_mfma_f32_16x16x32_bf16 v[90:93], v[134:137], v[222:225], v[90:93]
	v_mfma_f32_16x16x32_bf16 v[78:81], v[114:117], v[226:229], 0
	v_mfma_f32_16x16x32_bf16 v[78:81], v[126:129], v[230:233], v[78:81]
	v_mfma_f32_16x16x32_bf16 v[74:77], v[130:133], v[226:229], 0
	v_mfma_f32_16x16x32_bf16 v[74:77], v[134:137], v[230:233], v[74:77]
	v_mfma_f32_16x16x32_bf16 v[122:125], v[146:149], v[186:189], 0
	v_mfma_f32_16x16x32_bf16 v[122:125], v[150:153], v[194:197], v[122:125]
	v_mfma_f32_16x16x32_bf16 v[118:121], v[158:161], v[186:189], 0
	v_mfma_f32_16x16x32_bf16 v[118:121], v[182:185], v[194:197], v[118:121]
	v_mfma_f32_16x16x32_bf16 v[102:105], v[146:149], v[198:201], 0
	v_mfma_f32_16x16x32_bf16 v[102:105], v[150:153], v[214:217], v[102:105]
	v_mfma_f32_16x16x32_bf16 v[98:101], v[158:161], v[198:201], 0
	v_mfma_f32_16x16x32_bf16 v[98:101], v[182:185], v[214:217], v[98:101]
	v_mfma_f32_16x16x32_bf16 v[86:89], v[146:149], v[218:221], 0
	v_mfma_f32_16x16x32_bf16 v[86:89], v[150:153], v[222:225], v[86:89]
	v_mfma_f32_16x16x32_bf16 v[82:85], v[158:161], v[218:221], 0
	v_mfma_f32_16x16x32_bf16 v[82:85], v[182:185], v[222:225], v[82:85]
	v_mfma_f32_16x16x32_bf16 v[70:73], v[146:149], v[226:229], 0
	v_mfma_f32_16x16x32_bf16 v[70:73], v[150:153], v[230:233], v[70:73]
	v_mfma_f32_16x16x32_bf16 v[66:69], v[158:161], v[226:229], 0
	v_mfma_f32_16x16x32_bf16 v[66:69], v[182:185], v[230:233], v[66:69]
	s_barrier
	ds_read_b128 v[186:189], v193 offset:16384
	ds_read_b128 v[194:197], v193 offset:17408
	ds_read_b128 v[198:201], v193 offset:18432
	ds_read_b128 v[214:217], v193 offset:19456
	ds_read_b128 v[218:221], v193 offset:20480
	ds_read_b128 v[222:225], v193 offset:21504
	ds_read_b128 v[226:229], v193 offset:22528
	ds_read_b128 v[230:233], v193 offset:23552
	s_add_i32 m0, s46, 0x10000
	v_lshl_add_u64 v[162:163], s[20:21], 0, v[0:1]
	global_load_lds_dwordx4 v[162:163], off
	s_add_i32 m0, s46, 0x12000
	v_lshl_add_u64 v[202:203], v[162:163], 0, s[2:3]
	global_load_lds_dwordx4 v[202:203], off
	s_add_i32 m0, s46, 0x14000
	v_lshl_add_u64 v[202:203], v[162:163], 0, s[12:13]
	global_load_lds_dwordx4 v[202:203], off
	s_add_i32 m0, s46, 0x16000
	v_lshl_add_u64 v[202:203], v[162:163], 0, s[86:87]
	global_load_lds_dwordx4 v[202:203], off
	v_lshl_add_u64 v[202:203], s[60:61], 0, v[154:155]
	s_mov_b32 m0, s47
	v_lshl_add_u64 v[234:235], v[202:203], 0, s[2:3]
	global_load_lds_dwordx4 v[202:203], off
	s_mov_b32 m0, s68
	s_nop 0
	global_load_lds_dwordx4 v[234:235], off
	s_waitcnt vmcnt(8) lgkmcnt(0)
	s_barrier
	v_mfma_f32_16x16x32_bf16 v[62:65], v[114:117], v[186:189], 0
	v_mfma_f32_16x16x32_bf16 v[62:65], v[126:129], v[194:197], v[62:65]
	v_mfma_f32_16x16x32_bf16 v[58:61], v[130:133], v[186:189], 0
	v_mfma_f32_16x16x32_bf16 v[58:61], v[134:137], v[194:197], v[58:61]
	v_mfma_f32_16x16x32_bf16 v[46:49], v[114:117], v[198:201], 0
	v_mfma_f32_16x16x32_bf16 v[46:49], v[126:129], v[214:217], v[46:49]
	v_mfma_f32_16x16x32_bf16 v[42:45], v[130:133], v[198:201], 0
	v_mfma_f32_16x16x32_bf16 v[42:45], v[134:137], v[214:217], v[42:45]
	v_mfma_f32_16x16x32_bf16 v[30:33], v[114:117], v[218:221], 0
	v_mfma_f32_16x16x32_bf16 v[30:33], v[126:129], v[222:225], v[30:33]
	v_mfma_f32_16x16x32_bf16 v[26:29], v[130:133], v[218:221], 0
	v_mfma_f32_16x16x32_bf16 v[26:29], v[134:137], v[222:225], v[26:29]
	v_mfma_f32_16x16x32_bf16 v[14:17], v[114:117], v[226:229], 0
	v_mfma_f32_16x16x32_bf16 v[14:17], v[126:129], v[230:233], v[14:17]
	v_mfma_f32_16x16x32_bf16 v[10:13], v[130:133], v[226:229], 0
	v_mfma_f32_16x16x32_bf16 v[10:13], v[134:137], v[230:233], v[10:13]
	v_mfma_f32_16x16x32_bf16 v[54:57], v[146:149], v[186:189], 0
	v_mfma_f32_16x16x32_bf16 v[54:57], v[150:153], v[194:197], v[54:57]
	v_mfma_f32_16x16x32_bf16 v[50:53], v[158:161], v[186:189], 0
	v_mfma_f32_16x16x32_bf16 v[50:53], v[182:185], v[194:197], v[50:53]
	v_mfma_f32_16x16x32_bf16 v[38:41], v[146:149], v[198:201], 0
	v_mfma_f32_16x16x32_bf16 v[38:41], v[150:153], v[214:217], v[38:41]
	v_mfma_f32_16x16x32_bf16 v[34:37], v[158:161], v[198:201], 0
	v_mfma_f32_16x16x32_bf16 v[34:37], v[182:185], v[214:217], v[34:37]
	v_mfma_f32_16x16x32_bf16 v[22:25], v[146:149], v[218:221], 0
	v_mfma_f32_16x16x32_bf16 v[22:25], v[150:153], v[222:225], v[22:25]
	v_mfma_f32_16x16x32_bf16 v[18:21], v[158:161], v[218:221], 0
	v_mfma_f32_16x16x32_bf16 v[18:21], v[182:185], v[222:225], v[18:21]
	v_mfma_f32_16x16x32_bf16 v[6:9], v[146:149], v[226:229], 0
	v_mfma_f32_16x16x32_bf16 v[6:9], v[150:153], v[230:233], v[6:9]
	v_mfma_f32_16x16x32_bf16 v[2:5], v[158:161], v[226:229], 0
	v_mfma_f32_16x16x32_bf16 v[2:5], v[182:185], v[230:233], v[2:5]
	s_barrier
	ds_read_b128 v[114:117], v243 offset:32768
	ds_read_b128 v[126:129], v243 offset:33792
	ds_read_b128 v[130:133], v243 offset:34816
	ds_read_b128 v[134:137], v243 offset:35840
	ds_read_b128 v[146:149], v243 offset:49152
	ds_read_b128 v[150:153], v243 offset:50176
	ds_read_b128 v[158:161], v243 offset:51200
	ds_read_b128 v[182:185], v243 offset:52224
	ds_read_b128 v[186:189], v193 offset:32768
	ds_read_b128 v[194:197], v193 offset:33792
	ds_read_b128 v[198:201], v193 offset:34816
	ds_read_b128 v[214:217], v193 offset:35840
	ds_read_b128 v[218:221], v193 offset:36864
	ds_read_b128 v[222:225], v193 offset:37888
	ds_read_b128 v[226:229], v193 offset:38912
	ds_read_b128 v[230:233], v193 offset:39936
	s_mov_b32 m0, s69
	v_lshl_add_u64 v[234:235], v[202:203], 0, s[12:13]
	global_load_lds_dwordx4 v[234:235], off
	v_lshl_add_u64 v[234:235], v[202:203], 0, s[86:87]
	s_mov_b32 m0, s76
	s_nop 0
	global_load_lds_dwordx4 v[234:235], off
	s_waitcnt vmcnt(8) lgkmcnt(0)
	s_barrier
	v_mfma_f32_16x16x32_bf16 v[142:145], v[114:117], v[186:189], v[142:145]
	v_mfma_f32_16x16x32_bf16 v[142:145], v[126:129], v[194:197], v[142:145]
	v_mfma_f32_16x16x32_bf16 v[138:141], v[130:133], v[186:189], v[138:141]
	v_mfma_f32_16x16x32_bf16 v[138:141], v[134:137], v[194:197], v[138:141]
	v_mfma_f32_16x16x32_bf16 v[110:113], v[114:117], v[198:201], v[110:113]
	v_mfma_f32_16x16x32_bf16 v[110:113], v[126:129], v[214:217], v[110:113]
	v_mfma_f32_16x16x32_bf16 v[106:109], v[130:133], v[198:201], v[106:109]
	v_mfma_f32_16x16x32_bf16 v[106:109], v[134:137], v[214:217], v[106:109]
	v_mfma_f32_16x16x32_bf16 v[94:97], v[114:117], v[218:221], v[94:97]
	v_mfma_f32_16x16x32_bf16 v[94:97], v[126:129], v[222:225], v[94:97]
	v_mfma_f32_16x16x32_bf16 v[90:93], v[130:133], v[218:221], v[90:93]
	v_mfma_f32_16x16x32_bf16 v[90:93], v[134:137], v[222:225], v[90:93]
	v_mfma_f32_16x16x32_bf16 v[78:81], v[114:117], v[226:229], v[78:81]
	v_mfma_f32_16x16x32_bf16 v[78:81], v[126:129], v[230:233], v[78:81]
	v_mfma_f32_16x16x32_bf16 v[74:77], v[130:133], v[226:229], v[74:77]
	v_mfma_f32_16x16x32_bf16 v[74:77], v[134:137], v[230:233], v[74:77]
	v_mfma_f32_16x16x32_bf16 v[122:125], v[146:149], v[186:189], v[122:125]
	v_mfma_f32_16x16x32_bf16 v[122:125], v[150:153], v[194:197], v[122:125]
	v_mfma_f32_16x16x32_bf16 v[118:121], v[158:161], v[186:189], v[118:121]
	v_mfma_f32_16x16x32_bf16 v[118:121], v[182:185], v[194:197], v[118:121]
	v_mfma_f32_16x16x32_bf16 v[102:105], v[146:149], v[198:201], v[102:105]
	v_mfma_f32_16x16x32_bf16 v[102:105], v[150:153], v[214:217], v[102:105]
	v_mfma_f32_16x16x32_bf16 v[98:101], v[158:161], v[198:201], v[98:101]
	v_mfma_f32_16x16x32_bf16 v[98:101], v[182:185], v[214:217], v[98:101]
	v_mfma_f32_16x16x32_bf16 v[86:89], v[146:149], v[218:221], v[86:89]
	v_mfma_f32_16x16x32_bf16 v[86:89], v[150:153], v[222:225], v[86:89]
	v_mfma_f32_16x16x32_bf16 v[82:85], v[158:161], v[218:221], v[82:85]
	v_mfma_f32_16x16x32_bf16 v[82:85], v[182:185], v[222:225], v[82:85]
	v_mfma_f32_16x16x32_bf16 v[70:73], v[146:149], v[226:229], v[70:73]
	v_mfma_f32_16x16x32_bf16 v[70:73], v[150:153], v[230:233], v[70:73]
	v_mfma_f32_16x16x32_bf16 v[66:69], v[158:161], v[226:229], v[66:69]
	v_mfma_f32_16x16x32_bf16 v[66:69], v[182:185], v[230:233], v[66:69]
	s_barrier
	ds_read_b128 v[186:189], v193 offset:49152
	ds_read_b128 v[194:197], v193 offset:50176
	ds_read_b128 v[198:201], v193 offset:51200
	ds_read_b128 v[214:217], v193 offset:52224
	ds_read_b128 v[218:221], v193 offset:53248
	ds_read_b128 v[222:225], v193 offset:54272
	ds_read_b128 v[226:229], v193 offset:55296
	ds_read_b128 v[230:233], v193 offset:56320
	s_add_i32 m0, s46, 0x18000
	v_lshl_add_u64 v[234:235], v[162:163], 0, s[34:35]
	global_load_lds_dwordx4 v[234:235], off
	s_add_i32 m0, s46, 0x1a000
	v_lshl_add_u64 v[234:235], v[162:163], 0, s[96:97]
	global_load_lds_dwordx4 v[234:235], off
	v_lshl_add_u64 v[234:235], v[162:163], 0, vcc
	s_add_i32 m0, s46, 0x1c000
	v_lshl_add_u64 v[162:163], v[162:163], 0, s[0:1]
	global_load_lds_dwordx4 v[234:235], off
	s_add_i32 m0, s46, 0x1e000
	s_nop 0
	global_load_lds_dwordx4 v[162:163], off
	v_lshl_add_u64 v[162:163], v[202:203], 0, s[34:35]
	s_mov_b32 m0, s77
	s_nop 0
	global_load_lds_dwordx4 v[162:163], off
	v_lshl_add_u64 v[162:163], v[202:203], 0, s[96:97]
	s_mov_b32 m0, s78
	s_nop 0
	global_load_lds_dwordx4 v[162:163], off
	s_waitcnt vmcnt(8) lgkmcnt(0)
	s_barrier
	v_mfma_f32_16x16x32_bf16 v[62:65], v[114:117], v[186:189], v[62:65]
	v_mfma_f32_16x16x32_bf16 v[62:65], v[126:129], v[194:197], v[62:65]
	v_mfma_f32_16x16x32_bf16 v[58:61], v[130:133], v[186:189], v[58:61]
	v_mfma_f32_16x16x32_bf16 v[58:61], v[134:137], v[194:197], v[58:61]
	v_mfma_f32_16x16x32_bf16 v[46:49], v[114:117], v[198:201], v[46:49]
	v_mfma_f32_16x16x32_bf16 v[46:49], v[126:129], v[214:217], v[46:49]
	v_mfma_f32_16x16x32_bf16 v[42:45], v[130:133], v[198:201], v[42:45]
	v_mfma_f32_16x16x32_bf16 v[42:45], v[134:137], v[214:217], v[42:45]
	v_mfma_f32_16x16x32_bf16 v[30:33], v[114:117], v[218:221], v[30:33]
	v_mfma_f32_16x16x32_bf16 v[30:33], v[126:129], v[222:225], v[30:33]
	v_mfma_f32_16x16x32_bf16 v[26:29], v[130:133], v[218:221], v[26:29]
	v_mfma_f32_16x16x32_bf16 v[26:29], v[134:137], v[222:225], v[26:29]
	v_mfma_f32_16x16x32_bf16 v[14:17], v[114:117], v[226:229], v[14:17]
	v_mfma_f32_16x16x32_bf16 v[14:17], v[126:129], v[230:233], v[14:17]
	v_mfma_f32_16x16x32_bf16 v[10:13], v[130:133], v[226:229], v[10:13]
	v_mfma_f32_16x16x32_bf16 v[10:13], v[134:137], v[230:233], v[10:13]
	s_add_i32 s84, s84, 2
	s_add_u32 s56, s56, 0x100
	s_addc_u32 s57, s57, 0
	s_add_u32 s62, s62, 0x100
	s_addc_u32 s63, s63, 0
	v_mfma_f32_16x16x32_bf16 v[54:57], v[146:149], v[186:189], v[54:57]
	v_mfma_f32_16x16x32_bf16 v[54:57], v[150:153], v[194:197], v[54:57]
	v_mfma_f32_16x16x32_bf16 v[50:53], v[158:161], v[186:189], v[50:53]
	v_mfma_f32_16x16x32_bf16 v[50:53], v[182:185], v[194:197], v[50:53]
	v_mfma_f32_16x16x32_bf16 v[38:41], v[146:149], v[198:201], v[38:41]
	v_mfma_f32_16x16x32_bf16 v[38:41], v[150:153], v[214:217], v[38:41]
	v_mfma_f32_16x16x32_bf16 v[34:37], v[158:161], v[198:201], v[34:37]
	v_mfma_f32_16x16x32_bf16 v[34:37], v[182:185], v[214:217], v[34:37]
	v_mfma_f32_16x16x32_bf16 v[22:25], v[146:149], v[218:221], v[22:25]
	v_mfma_f32_16x16x32_bf16 v[22:25], v[150:153], v[222:225], v[22:25]
	v_mfma_f32_16x16x32_bf16 v[18:21], v[158:161], v[218:221], v[18:21]
	v_mfma_f32_16x16x32_bf16 v[18:21], v[182:185], v[222:225], v[18:21]
	v_mfma_f32_16x16x32_bf16 v[6:9], v[146:149], v[226:229], v[6:9]
	v_mfma_f32_16x16x32_bf16 v[6:9], v[150:153], v[230:233], v[6:9]
	v_mfma_f32_16x16x32_bf16 v[2:5], v[158:161], v[226:229], v[2:5]
	v_mfma_f32_16x16x32_bf16 v[2:5], v[182:185], v[230:233], v[2:5]
	s_barrier
	s_branch .LBB0_446
	.p2alignl 6, 3212836864
.LBB0_446:
	ds_read_b128 v[114:117], v243
	ds_read_b128 v[126:129], v243 offset:1024
	ds_read_b128 v[130:133], v243 offset:2048
	ds_read_b128 v[134:137], v243 offset:3072
	ds_read_b128 v[146:149], v243 offset:16384
	ds_read_b128 v[150:153], v243 offset:17408
	ds_read_b128 v[158:161], v243 offset:18432
	ds_read_b128 v[182:185], v243 offset:19456
	ds_read_b128 v[186:189], v193
	ds_read_b128 v[194:197], v193 offset:1024
	ds_read_b128 v[198:201], v193 offset:2048
	ds_read_b128 v[214:217], v193 offset:3072
	ds_read_b128 v[218:221], v193 offset:4096
	ds_read_b128 v[222:225], v193 offset:5120
	ds_read_b128 v[226:229], v193 offset:6144
	ds_read_b128 v[230:233], v193 offset:7168
	s_add_u32 s20, s56, 0xfff50080
	s_addc_u32 s21, s57, -1
	s_cmp_eq_u32 s84, 40
	s_cselect_b32 s61, s49, s21
	s_cselect_b32 s60, s48, s20
	s_cselect_b32 s21, s51, s63
	s_cselect_b32 s20, s50, s62
	s_add_i32 m0, s47, 0xc000
	v_lshl_add_u64 v[162:163], s[56:57], 0, v[156:157]
	global_load_lds_dwordx4 v[162:163], off
	s_add_i32 m0, s47, 0xe000
	v_lshl_add_u64 v[162:163], v[162:163], 0, s[2:3]
	global_load_lds_dwordx4 v[162:163], off
	s_waitcnt vmcnt(8) lgkmcnt(0)
	s_barrier
	v_mfma_f32_16x16x32_bf16 v[142:145], v[114:117], v[186:189], v[142:145]
	v_mfma_f32_16x16x32_bf16 v[142:145], v[126:129], v[194:197], v[142:145]
	v_mfma_f32_16x16x32_bf16 v[138:141], v[130:133], v[186:189], v[138:141]
	v_mfma_f32_16x16x32_bf16 v[138:141], v[134:137], v[194:197], v[138:141]
	v_mfma_f32_16x16x32_bf16 v[110:113], v[114:117], v[198:201], v[110:113]
	v_mfma_f32_16x16x32_bf16 v[110:113], v[126:129], v[214:217], v[110:113]
	v_mfma_f32_16x16x32_bf16 v[106:109], v[130:133], v[198:201], v[106:109]
	v_mfma_f32_16x16x32_bf16 v[106:109], v[134:137], v[214:217], v[106:109]
	v_mfma_f32_16x16x32_bf16 v[94:97], v[114:117], v[218:221], v[94:97]
	v_mfma_f32_16x16x32_bf16 v[94:97], v[126:129], v[222:225], v[94:97]
	v_mfma_f32_16x16x32_bf16 v[90:93], v[130:133], v[218:221], v[90:93]
	v_mfma_f32_16x16x32_bf16 v[90:93], v[134:137], v[222:225], v[90:93]
	v_mfma_f32_16x16x32_bf16 v[78:81], v[114:117], v[226:229], v[78:81]
	v_mfma_f32_16x16x32_bf16 v[78:81], v[126:129], v[230:233], v[78:81]
	v_mfma_f32_16x16x32_bf16 v[74:77], v[130:133], v[226:229], v[74:77]
	v_mfma_f32_16x16x32_bf16 v[74:77], v[134:137], v[230:233], v[74:77]
	v_mfma_f32_16x16x32_bf16 v[122:125], v[146:149], v[186:189], v[122:125]
	v_mfma_f32_16x16x32_bf16 v[122:125], v[150:153], v[194:197], v[122:125]
	v_mfma_f32_16x16x32_bf16 v[118:121], v[158:161], v[186:189], v[118:121]
	v_mfma_f32_16x16x32_bf16 v[118:121], v[182:185], v[194:197], v[118:121]
	v_mfma_f32_16x16x32_bf16 v[102:105], v[146:149], v[198:201], v[102:105]
	v_mfma_f32_16x16x32_bf16 v[102:105], v[150:153], v[214:217], v[102:105]
	v_mfma_f32_16x16x32_bf16 v[98:101], v[158:161], v[198:201], v[98:101]
	v_mfma_f32_16x16x32_bf16 v[98:101], v[182:185], v[214:217], v[98:101]
	v_mfma_f32_16x16x32_bf16 v[86:89], v[146:149], v[218:221], v[86:89]
	v_mfma_f32_16x16x32_bf16 v[86:89], v[150:153], v[222:225], v[86:89]
	v_mfma_f32_16x16x32_bf16 v[82:85], v[158:161], v[218:221], v[82:85]
	v_mfma_f32_16x16x32_bf16 v[82:85], v[182:185], v[222:225], v[82:85]
	v_mfma_f32_16x16x32_bf16 v[70:73], v[146:149], v[226:229], v[70:73]
	v_mfma_f32_16x16x32_bf16 v[70:73], v[150:153], v[230:233], v[70:73]
	v_mfma_f32_16x16x32_bf16 v[66:69], v[158:161], v[226:229], v[66:69]
	v_mfma_f32_16x16x32_bf16 v[66:69], v[182:185], v[230:233], v[66:69]
	s_barrier
	ds_read_b128 v[186:189], v193 offset:16384
	ds_read_b128 v[194:197], v193 offset:17408
	ds_read_b128 v[198:201], v193 offset:18432
	ds_read_b128 v[214:217], v193 offset:19456
	ds_read_b128 v[218:221], v193 offset:20480
	ds_read_b128 v[222:225], v193 offset:21504
	ds_read_b128 v[226:229], v193 offset:22528
	ds_read_b128 v[230:233], v193 offset:23552
	s_add_i32 m0, s46, 0x10000
	v_lshl_add_u64 v[162:163], s[20:21], 0, v[0:1]
	global_load_lds_dwordx4 v[162:163], off
	s_add_i32 m0, s46, 0x12000
	v_lshl_add_u64 v[202:203], v[162:163], 0, s[2:3]
	global_load_lds_dwordx4 v[202:203], off
	s_add_i32 m0, s46, 0x14000
	v_lshl_add_u64 v[202:203], v[162:163], 0, s[12:13]
	global_load_lds_dwordx4 v[202:203], off
	s_add_i32 m0, s46, 0x16000
	v_lshl_add_u64 v[202:203], v[162:163], 0, s[86:87]
	global_load_lds_dwordx4 v[202:203], off
	v_lshl_add_u64 v[202:203], s[60:61], 0, v[154:155]
	s_mov_b32 m0, s47
	v_lshl_add_u64 v[234:235], v[202:203], 0, s[2:3]
	global_load_lds_dwordx4 v[202:203], off
	s_mov_b32 m0, s68
	s_nop 0
	global_load_lds_dwordx4 v[234:235], off
	s_waitcnt vmcnt(8) lgkmcnt(0)
	s_barrier
	v_mfma_f32_16x16x32_bf16 v[62:65], v[114:117], v[186:189], v[62:65]
	v_mfma_f32_16x16x32_bf16 v[62:65], v[126:129], v[194:197], v[62:65]
	v_mfma_f32_16x16x32_bf16 v[58:61], v[130:133], v[186:189], v[58:61]
	v_mfma_f32_16x16x32_bf16 v[58:61], v[134:137], v[194:197], v[58:61]
	v_mfma_f32_16x16x32_bf16 v[46:49], v[114:117], v[198:201], v[46:49]
	v_mfma_f32_16x16x32_bf16 v[46:49], v[126:129], v[214:217], v[46:49]
	v_mfma_f32_16x16x32_bf16 v[42:45], v[130:133], v[198:201], v[42:45]
	v_mfma_f32_16x16x32_bf16 v[42:45], v[134:137], v[214:217], v[42:45]
	v_mfma_f32_16x16x32_bf16 v[30:33], v[114:117], v[218:221], v[30:33]
	v_mfma_f32_16x16x32_bf16 v[30:33], v[126:129], v[222:225], v[30:33]
	v_mfma_f32_16x16x32_bf16 v[26:29], v[130:133], v[218:221], v[26:29]
	v_mfma_f32_16x16x32_bf16 v[26:29], v[134:137], v[222:225], v[26:29]
	v_mfma_f32_16x16x32_bf16 v[14:17], v[114:117], v[226:229], v[14:17]
	v_mfma_f32_16x16x32_bf16 v[14:17], v[126:129], v[230:233], v[14:17]
	v_mfma_f32_16x16x32_bf16 v[10:13], v[130:133], v[226:229], v[10:13]
	v_mfma_f32_16x16x32_bf16 v[10:13], v[134:137], v[230:233], v[10:13]
	v_mfma_f32_16x16x32_bf16 v[54:57], v[146:149], v[186:189], v[54:57]
	v_mfma_f32_16x16x32_bf16 v[54:57], v[150:153], v[194:197], v[54:57]
	v_mfma_f32_16x16x32_bf16 v[50:53], v[158:161], v[186:189], v[50:53]
	v_mfma_f32_16x16x32_bf16 v[50:53], v[182:185], v[194:197], v[50:53]
	v_mfma_f32_16x16x32_bf16 v[38:41], v[146:149], v[198:201], v[38:41]
	v_mfma_f32_16x16x32_bf16 v[38:41], v[150:153], v[214:217], v[38:41]
	v_mfma_f32_16x16x32_bf16 v[34:37], v[158:161], v[198:201], v[34:37]
	v_mfma_f32_16x16x32_bf16 v[34:37], v[182:185], v[214:217], v[34:37]
	v_mfma_f32_16x16x32_bf16 v[22:25], v[146:149], v[218:221], v[22:25]
	v_mfma_f32_16x16x32_bf16 v[22:25], v[150:153], v[222:225], v[22:25]
	v_mfma_f32_16x16x32_bf16 v[18:21], v[158:161], v[218:221], v[18:21]
	v_mfma_f32_16x16x32_bf16 v[18:21], v[182:185], v[222:225], v[18:21]
	v_mfma_f32_16x16x32_bf16 v[6:9], v[146:149], v[226:229], v[6:9]
	v_mfma_f32_16x16x32_bf16 v[6:9], v[150:153], v[230:233], v[6:9]
	v_mfma_f32_16x16x32_bf16 v[2:5], v[158:161], v[226:229], v[2:5]
	v_mfma_f32_16x16x32_bf16 v[2:5], v[182:185], v[230:233], v[2:5]
	s_barrier
	ds_read_b128 v[114:117], v243 offset:32768
	ds_read_b128 v[126:129], v243 offset:33792
	ds_read_b128 v[130:133], v243 offset:34816
	ds_read_b128 v[134:137], v243 offset:35840
	ds_read_b128 v[146:149], v243 offset:49152
	ds_read_b128 v[150:153], v243 offset:50176
	ds_read_b128 v[158:161], v243 offset:51200
	ds_read_b128 v[182:185], v243 offset:52224
	ds_read_b128 v[186:189], v193 offset:32768
	ds_read_b128 v[194:197], v193 offset:33792
	ds_read_b128 v[198:201], v193 offset:34816
	ds_read_b128 v[214:217], v193 offset:35840
	ds_read_b128 v[218:221], v193 offset:36864
	ds_read_b128 v[222:225], v193 offset:37888
	ds_read_b128 v[226:229], v193 offset:38912
	ds_read_b128 v[230:233], v193 offset:39936
	s_mov_b32 m0, s69
	v_lshl_add_u64 v[234:235], v[202:203], 0, s[12:13]
	global_load_lds_dwordx4 v[234:235], off
	v_lshl_add_u64 v[234:235], v[202:203], 0, s[86:87]
	s_mov_b32 m0, s76
	s_nop 0
	global_load_lds_dwordx4 v[234:235], off
	s_waitcnt vmcnt(8) lgkmcnt(0)
	s_barrier
	v_mfma_f32_16x16x32_bf16 v[142:145], v[114:117], v[186:189], v[142:145]
	v_mfma_f32_16x16x32_bf16 v[142:145], v[126:129], v[194:197], v[142:145]
	v_mfma_f32_16x16x32_bf16 v[138:141], v[130:133], v[186:189], v[138:141]
	v_mfma_f32_16x16x32_bf16 v[138:141], v[134:137], v[194:197], v[138:141]
	v_mfma_f32_16x16x32_bf16 v[110:113], v[114:117], v[198:201], v[110:113]
	v_mfma_f32_16x16x32_bf16 v[110:113], v[126:129], v[214:217], v[110:113]
	v_mfma_f32_16x16x32_bf16 v[106:109], v[130:133], v[198:201], v[106:109]
	v_mfma_f32_16x16x32_bf16 v[106:109], v[134:137], v[214:217], v[106:109]
	v_mfma_f32_16x16x32_bf16 v[94:97], v[114:117], v[218:221], v[94:97]
	v_mfma_f32_16x16x32_bf16 v[94:97], v[126:129], v[222:225], v[94:97]
	v_mfma_f32_16x16x32_bf16 v[90:93], v[130:133], v[218:221], v[90:93]
	v_mfma_f32_16x16x32_bf16 v[90:93], v[134:137], v[222:225], v[90:93]
	v_mfma_f32_16x16x32_bf16 v[78:81], v[114:117], v[226:229], v[78:81]
	v_mfma_f32_16x16x32_bf16 v[78:81], v[126:129], v[230:233], v[78:81]
	v_mfma_f32_16x16x32_bf16 v[74:77], v[130:133], v[226:229], v[74:77]
	v_mfma_f32_16x16x32_bf16 v[74:77], v[134:137], v[230:233], v[74:77]
	v_mfma_f32_16x16x32_bf16 v[122:125], v[146:149], v[186:189], v[122:125]
	v_mfma_f32_16x16x32_bf16 v[122:125], v[150:153], v[194:197], v[122:125]
	v_mfma_f32_16x16x32_bf16 v[118:121], v[158:161], v[186:189], v[118:121]
	v_mfma_f32_16x16x32_bf16 v[118:121], v[182:185], v[194:197], v[118:121]
	v_mfma_f32_16x16x32_bf16 v[102:105], v[146:149], v[198:201], v[102:105]
	v_mfma_f32_16x16x32_bf16 v[102:105], v[150:153], v[214:217], v[102:105]
	v_mfma_f32_16x16x32_bf16 v[98:101], v[158:161], v[198:201], v[98:101]
	v_mfma_f32_16x16x32_bf16 v[98:101], v[182:185], v[214:217], v[98:101]
	v_mfma_f32_16x16x32_bf16 v[86:89], v[146:149], v[218:221], v[86:89]
	v_mfma_f32_16x16x32_bf16 v[86:89], v[150:153], v[222:225], v[86:89]
	v_mfma_f32_16x16x32_bf16 v[82:85], v[158:161], v[218:221], v[82:85]
	v_mfma_f32_16x16x32_bf16 v[82:85], v[182:185], v[222:225], v[82:85]
	v_mfma_f32_16x16x32_bf16 v[70:73], v[146:149], v[226:229], v[70:73]
	v_mfma_f32_16x16x32_bf16 v[70:73], v[150:153], v[230:233], v[70:73]
	v_mfma_f32_16x16x32_bf16 v[66:69], v[158:161], v[226:229], v[66:69]
	v_mfma_f32_16x16x32_bf16 v[66:69], v[182:185], v[230:233], v[66:69]
	s_barrier
	ds_read_b128 v[186:189], v193 offset:49152
	ds_read_b128 v[194:197], v193 offset:50176
	ds_read_b128 v[198:201], v193 offset:51200
	ds_read_b128 v[214:217], v193 offset:52224
	ds_read_b128 v[218:221], v193 offset:53248
	ds_read_b128 v[222:225], v193 offset:54272
	ds_read_b128 v[226:229], v193 offset:55296
	ds_read_b128 v[230:233], v193 offset:56320
	s_add_i32 m0, s46, 0x18000
	v_lshl_add_u64 v[234:235], v[162:163], 0, s[34:35]
	global_load_lds_dwordx4 v[234:235], off
	s_add_i32 m0, s46, 0x1a000
	v_lshl_add_u64 v[234:235], v[162:163], 0, s[96:97]
	global_load_lds_dwordx4 v[234:235], off
	v_lshl_add_u64 v[234:235], v[162:163], 0, vcc
	s_add_i32 m0, s46, 0x1c000
	v_lshl_add_u64 v[162:163], v[162:163], 0, s[0:1]
	global_load_lds_dwordx4 v[234:235], off
	s_add_i32 m0, s46, 0x1e000
	s_nop 0
	global_load_lds_dwordx4 v[162:163], off
	v_lshl_add_u64 v[162:163], v[202:203], 0, s[34:35]
	s_mov_b32 m0, s77
	s_nop 0
	global_load_lds_dwordx4 v[162:163], off
	v_lshl_add_u64 v[162:163], v[202:203], 0, s[96:97]
	s_mov_b32 m0, s78
	s_nop 0
	global_load_lds_dwordx4 v[162:163], off
	s_waitcnt vmcnt(8) lgkmcnt(0)
	s_barrier
	v_mfma_f32_16x16x32_bf16 v[62:65], v[114:117], v[186:189], v[62:65]
	v_mfma_f32_16x16x32_bf16 v[62:65], v[126:129], v[194:197], v[62:65]
	v_mfma_f32_16x16x32_bf16 v[58:61], v[130:133], v[186:189], v[58:61]
	v_mfma_f32_16x16x32_bf16 v[58:61], v[134:137], v[194:197], v[58:61]
	v_mfma_f32_16x16x32_bf16 v[46:49], v[114:117], v[198:201], v[46:49]
	v_mfma_f32_16x16x32_bf16 v[46:49], v[126:129], v[214:217], v[46:49]
	v_mfma_f32_16x16x32_bf16 v[42:45], v[130:133], v[198:201], v[42:45]
	v_mfma_f32_16x16x32_bf16 v[42:45], v[134:137], v[214:217], v[42:45]
	v_mfma_f32_16x16x32_bf16 v[30:33], v[114:117], v[218:221], v[30:33]
	v_mfma_f32_16x16x32_bf16 v[30:33], v[126:129], v[222:225], v[30:33]
	v_mfma_f32_16x16x32_bf16 v[26:29], v[130:133], v[218:221], v[26:29]
	v_mfma_f32_16x16x32_bf16 v[26:29], v[134:137], v[222:225], v[26:29]
	v_mfma_f32_16x16x32_bf16 v[14:17], v[114:117], v[226:229], v[14:17]
	v_mfma_f32_16x16x32_bf16 v[14:17], v[126:129], v[230:233], v[14:17]
	v_mfma_f32_16x16x32_bf16 v[10:13], v[130:133], v[226:229], v[10:13]
	v_mfma_f32_16x16x32_bf16 v[10:13], v[134:137], v[230:233], v[10:13]
	s_add_i32 s84, s84, 2
	s_add_u32 s56, s56, 0x100
	s_addc_u32 s57, s57, 0
	s_add_u32 s62, s62, 0x100
	s_addc_u32 s63, s63, 0
	v_mfma_f32_16x16x32_bf16 v[54:57], v[146:149], v[186:189], v[54:57]
	v_mfma_f32_16x16x32_bf16 v[54:57], v[150:153], v[194:197], v[54:57]
	v_mfma_f32_16x16x32_bf16 v[50:53], v[158:161], v[186:189], v[50:53]
	v_mfma_f32_16x16x32_bf16 v[50:53], v[182:185], v[194:197], v[50:53]
	v_mfma_f32_16x16x32_bf16 v[38:41], v[146:149], v[198:201], v[38:41]
	v_mfma_f32_16x16x32_bf16 v[38:41], v[150:153], v[214:217], v[38:41]
	v_mfma_f32_16x16x32_bf16 v[34:37], v[158:161], v[198:201], v[34:37]
	v_mfma_f32_16x16x32_bf16 v[34:37], v[182:185], v[214:217], v[34:37]
	v_mfma_f32_16x16x32_bf16 v[22:25], v[146:149], v[218:221], v[22:25]
	v_mfma_f32_16x16x32_bf16 v[22:25], v[150:153], v[222:225], v[22:25]
	v_mfma_f32_16x16x32_bf16 v[18:21], v[158:161], v[218:221], v[18:21]
	v_mfma_f32_16x16x32_bf16 v[18:21], v[182:185], v[222:225], v[18:21]
	v_mfma_f32_16x16x32_bf16 v[6:9], v[146:149], v[226:229], v[6:9]
	v_mfma_f32_16x16x32_bf16 v[6:9], v[150:153], v[230:233], v[6:9]
	v_mfma_f32_16x16x32_bf16 v[2:5], v[158:161], v[226:229], v[2:5]
	v_mfma_f32_16x16x32_bf16 v[2:5], v[182:185], v[230:233], v[2:5]
	s_barrier
	s_cmp_gt_u32 s84, 41
	s_cbranch_scc0 .LBB0_446
	s_setprio 0
	s_and_b64 vcc, exec, s[40:41]
	s_cbranch_vccz .LBB0_449
	s_barrier

.Lmid1_488:
	s_add_u32 s20, s68, 0xfffc0080
	s_addc_u32 s21, s69, -1
	s_cmp_eq_u32 s97, 12
	s_cselect_b32 s77, s57, s21
	s_cselect_b32 s76, s86, s20
	s_cselect_b32 s21, s51, s96
	s_cselect_b32 s20, s87, s91
	s_add_i32 m0, s43, 0xc000
	v_lshl_add_u64 v[202:203], s[68:69], 0, v[132:133]
	global_load_lds_dwordx4 v[202:203], off
	s_add_i32 m0, s43, 0xe000
	v_lshl_add_u64 v[202:203], v[202:203], 0, s[72:73]
	global_load_lds_dwordx4 v[202:203], off
	s_waitcnt vmcnt(8) lgkmcnt(0)
	s_barrier
	v_mfma_f32_16x16x32_bf16 v[126:129], v[134:137], v[190:193], 0
	v_mfma_f32_16x16x32_bf16 v[126:129], v[144:147], v[194:197], v[126:129]
	v_mfma_f32_16x16x32_bf16 v[114:117], v[148:151], v[190:193], 0
	v_mfma_f32_16x16x32_bf16 v[114:117], v[152:155], v[194:197], v[114:117]
	v_mfma_f32_16x16x32_bf16 v[110:113], v[134:137], v[198:201], 0
	v_mfma_f32_16x16x32_bf16 v[110:113], v[144:147], v[214:217], v[110:113]
	v_mfma_f32_16x16x32_bf16 v[98:101], v[148:151], v[198:201], 0
	v_mfma_f32_16x16x32_bf16 v[98:101], v[152:155], v[214:217], v[98:101]
	v_mfma_f32_16x16x32_bf16 v[94:97], v[134:137], v[218:221], 0
	v_mfma_f32_16x16x32_bf16 v[94:97], v[144:147], v[222:225], v[94:97]
	v_mfma_f32_16x16x32_bf16 v[82:85], v[148:151], v[218:221], 0
	v_mfma_f32_16x16x32_bf16 v[82:85], v[152:155], v[222:225], v[82:85]
	v_mfma_f32_16x16x32_bf16 v[78:81], v[134:137], v[226:229], 0
	v_mfma_f32_16x16x32_bf16 v[78:81], v[144:147], v[230:233], v[78:81]
	v_mfma_f32_16x16x32_bf16 v[66:69], v[148:151], v[226:229], 0
	v_mfma_f32_16x16x32_bf16 v[66:69], v[152:155], v[230:233], v[66:69]
	v_mfma_f32_16x16x32_bf16 v[122:125], v[156:159], v[190:193], 0
	v_mfma_f32_16x16x32_bf16 v[122:125], v[160:163], v[194:197], v[122:125]
	v_mfma_f32_16x16x32_bf16 v[118:121], v[182:185], v[190:193], 0
	v_mfma_f32_16x16x32_bf16 v[118:121], v[186:189], v[194:197], v[118:121]
	v_mfma_f32_16x16x32_bf16 v[106:109], v[156:159], v[198:201], 0
	v_mfma_f32_16x16x32_bf16 v[106:109], v[160:163], v[214:217], v[106:109]
	v_mfma_f32_16x16x32_bf16 v[102:105], v[182:185], v[198:201], 0
	v_mfma_f32_16x16x32_bf16 v[102:105], v[186:189], v[214:217], v[102:105]
	v_mfma_f32_16x16x32_bf16 v[90:93], v[156:159], v[218:221], 0
	v_mfma_f32_16x16x32_bf16 v[90:93], v[160:163], v[222:225], v[90:93]
	v_mfma_f32_16x16x32_bf16 v[86:89], v[182:185], v[218:221], 0
	v_mfma_f32_16x16x32_bf16 v[86:89], v[186:189], v[222:225], v[86:89]
	v_mfma_f32_16x16x32_bf16 v[74:77], v[156:159], v[226:229], 0
	v_mfma_f32_16x16x32_bf16 v[74:77], v[160:163], v[230:233], v[74:77]
	v_mfma_f32_16x16x32_bf16 v[70:73], v[182:185], v[226:229], 0
	v_mfma_f32_16x16x32_bf16 v[70:73], v[186:189], v[230:233], v[70:73]
	s_barrier
	ds_read_b128 v[190:193], v142 offset:16384
	ds_read_b128 v[194:197], v142 offset:17408
	ds_read_b128 v[198:201], v142 offset:18432
	ds_read_b128 v[214:217], v142 offset:19456
	ds_read_b128 v[218:221], v142 offset:20480
	ds_read_b128 v[222:225], v142 offset:21504
	ds_read_b128 v[226:229], v142 offset:22528
	ds_read_b128 v[230:233], v142 offset:23552
	s_add_i32 m0, s14, 0x10000
	v_lshl_add_u64 v[202:203], s[20:21], 0, v[0:1]
	global_load_lds_dwordx4 v[202:203], off
	s_add_i32 m0, s14, 0x12000
	v_lshl_add_u64 v[234:235], v[202:203], 0, s[72:73]
	global_load_lds_dwordx4 v[234:235], off
	s_add_i32 m0, s14, 0x14000
	v_lshl_add_u64 v[234:235], v[202:203], 0, s[28:29]
	global_load_lds_dwordx4 v[234:235], off
	s_add_i32 m0, s14, 0x16000
	v_lshl_add_u64 v[234:235], v[202:203], 0, s[82:83]
	global_load_lds_dwordx4 v[234:235], off
	v_lshl_add_u64 v[234:235], s[76:77], 0, v[130:131]
	s_mov_b32 m0, s43
	v_lshl_add_u64 v[236:237], v[234:235], 0, s[72:73]
	global_load_lds_dwordx4 v[234:235], off
	s_mov_b32 m0, s46
	s_nop 0
	global_load_lds_dwordx4 v[236:237], off
	s_waitcnt vmcnt(8) lgkmcnt(0)
	s_barrier
	v_mfma_f32_16x16x32_bf16 v[62:65], v[134:137], v[190:193], 0
	v_mfma_f32_16x16x32_bf16 v[62:65], v[144:147], v[194:197], v[62:65]
	v_mfma_f32_16x16x32_bf16 v[50:53], v[148:151], v[190:193], 0
	v_mfma_f32_16x16x32_bf16 v[50:53], v[152:155], v[194:197], v[50:53]
	v_mfma_f32_16x16x32_bf16 v[46:49], v[134:137], v[198:201], 0
	v_mfma_f32_16x16x32_bf16 v[46:49], v[144:147], v[214:217], v[46:49]
	v_mfma_f32_16x16x32_bf16 v[34:37], v[148:151], v[198:201], 0
	v_mfma_f32_16x16x32_bf16 v[34:37], v[152:155], v[214:217], v[34:37]
	v_mfma_f32_16x16x32_bf16 v[30:33], v[134:137], v[218:221], 0
	v_mfma_f32_16x16x32_bf16 v[30:33], v[144:147], v[222:225], v[30:33]
	v_mfma_f32_16x16x32_bf16 v[18:21], v[148:151], v[218:221], 0
	v_mfma_f32_16x16x32_bf16 v[18:21], v[152:155], v[222:225], v[18:21]
	v_mfma_f32_16x16x32_bf16 v[14:17], v[134:137], v[226:229], 0
	v_mfma_f32_16x16x32_bf16 v[14:17], v[144:147], v[230:233], v[14:17]
	v_mfma_f32_16x16x32_bf16 v[6:9], v[148:151], v[226:229], 0
	v_mfma_f32_16x16x32_bf16 v[6:9], v[152:155], v[230:233], v[6:9]
	v_mfma_f32_16x16x32_bf16 v[58:61], v[156:159], v[190:193], 0
	v_mfma_f32_16x16x32_bf16 v[58:61], v[160:163], v[194:197], v[58:61]
	v_mfma_f32_16x16x32_bf16 v[54:57], v[182:185], v[190:193], 0
	v_mfma_f32_16x16x32_bf16 v[54:57], v[186:189], v[194:197], v[54:57]
	v_mfma_f32_16x16x32_bf16 v[42:45], v[156:159], v[198:201], 0
	v_mfma_f32_16x16x32_bf16 v[42:45], v[160:163], v[214:217], v[42:45]
	v_mfma_f32_16x16x32_bf16 v[38:41], v[182:185], v[198:201], 0
	v_mfma_f32_16x16x32_bf16 v[38:41], v[186:189], v[214:217], v[38:41]
	v_mfma_f32_16x16x32_bf16 v[26:29], v[156:159], v[218:221], 0
	v_mfma_f32_16x16x32_bf16 v[26:29], v[160:163], v[222:225], v[26:29]
	v_mfma_f32_16x16x32_bf16 v[22:25], v[182:185], v[218:221], 0
	v_mfma_f32_16x16x32_bf16 v[22:25], v[186:189], v[222:225], v[22:25]
	v_mfma_f32_16x16x32_bf16 v[10:13], v[156:159], v[226:229], 0
	v_mfma_f32_16x16x32_bf16 v[10:13], v[160:163], v[230:233], v[10:13]
	v_mfma_f32_16x16x32_bf16 v[2:5], v[182:185], v[226:229], 0
	v_mfma_f32_16x16x32_bf16 v[2:5], v[186:189], v[230:233], v[2:5]
	s_barrier
	ds_read_b128 v[134:137], v243 offset:32768
	ds_read_b128 v[144:147], v243 offset:33792
	ds_read_b128 v[148:151], v243 offset:34816
	ds_read_b128 v[152:155], v243 offset:35840
	ds_read_b128 v[156:159], v243 offset:49152
	ds_read_b128 v[160:163], v243 offset:50176
	ds_read_b128 v[182:185], v243 offset:51200
	ds_read_b128 v[186:189], v243 offset:52224
	ds_read_b128 v[190:193], v142 offset:32768
	ds_read_b128 v[194:197], v142 offset:33792
	ds_read_b128 v[198:201], v142 offset:34816
	ds_read_b128 v[214:217], v142 offset:35840
	ds_read_b128 v[218:221], v142 offset:36864
	ds_read_b128 v[222:225], v142 offset:37888
	ds_read_b128 v[226:229], v142 offset:38912
	ds_read_b128 v[230:233], v142 offset:39936
	s_mov_b32 m0, s47
	v_lshl_add_u64 v[236:237], v[234:235], 0, s[28:29]
	global_load_lds_dwordx4 v[236:237], off
	v_lshl_add_u64 v[236:237], v[234:235], 0, s[82:83]
	s_mov_b32 m0, s78
	s_nop 0
	global_load_lds_dwordx4 v[236:237], off
	s_waitcnt vmcnt(8) lgkmcnt(0)
	s_barrier
	v_mfma_f32_16x16x32_bf16 v[126:129], v[134:137], v[190:193], v[126:129]
	v_mfma_f32_16x16x32_bf16 v[126:129], v[144:147], v[194:197], v[126:129]
	v_mfma_f32_16x16x32_bf16 v[114:117], v[148:151], v[190:193], v[114:117]
	v_mfma_f32_16x16x32_bf16 v[114:117], v[152:155], v[194:197], v[114:117]
	v_mfma_f32_16x16x32_bf16 v[110:113], v[134:137], v[198:201], v[110:113]
	v_mfma_f32_16x16x32_bf16 v[110:113], v[144:147], v[214:217], v[110:113]
	v_mfma_f32_16x16x32_bf16 v[98:101], v[148:151], v[198:201], v[98:101]
	v_mfma_f32_16x16x32_bf16 v[98:101], v[152:155], v[214:217], v[98:101]
	v_mfma_f32_16x16x32_bf16 v[94:97], v[134:137], v[218:221], v[94:97]
	v_mfma_f32_16x16x32_bf16 v[94:97], v[144:147], v[222:225], v[94:97]
	v_mfma_f32_16x16x32_bf16 v[82:85], v[148:151], v[218:221], v[82:85]
	v_mfma_f32_16x16x32_bf16 v[82:85], v[152:155], v[222:225], v[82:85]
	v_mfma_f32_16x16x32_bf16 v[78:81], v[134:137], v[226:229], v[78:81]
	v_mfma_f32_16x16x32_bf16 v[78:81], v[144:147], v[230:233], v[78:81]
	v_mfma_f32_16x16x32_bf16 v[66:69], v[148:151], v[226:229], v[66:69]
	v_mfma_f32_16x16x32_bf16 v[66:69], v[152:155], v[230:233], v[66:69]
	v_mfma_f32_16x16x32_bf16 v[122:125], v[156:159], v[190:193], v[122:125]
	v_mfma_f32_16x16x32_bf16 v[122:125], v[160:163], v[194:197], v[122:125]
	v_mfma_f32_16x16x32_bf16 v[118:121], v[182:185], v[190:193], v[118:121]
	v_mfma_f32_16x16x32_bf16 v[118:121], v[186:189], v[194:197], v[118:121]
	v_mfma_f32_16x16x32_bf16 v[106:109], v[156:159], v[198:201], v[106:109]
	v_mfma_f32_16x16x32_bf16 v[106:109], v[160:163], v[214:217], v[106:109]
	v_mfma_f32_16x16x32_bf16 v[102:105], v[182:185], v[198:201], v[102:105]
	v_mfma_f32_16x16x32_bf16 v[102:105], v[186:189], v[214:217], v[102:105]
	v_mfma_f32_16x16x32_bf16 v[90:93], v[156:159], v[218:221], v[90:93]
	v_mfma_f32_16x16x32_bf16 v[90:93], v[160:163], v[222:225], v[90:93]
	v_mfma_f32_16x16x32_bf16 v[86:89], v[182:185], v[218:221], v[86:89]
	v_mfma_f32_16x16x32_bf16 v[86:89], v[186:189], v[222:225], v[86:89]
	v_mfma_f32_16x16x32_bf16 v[74:77], v[156:159], v[226:229], v[74:77]
	v_mfma_f32_16x16x32_bf16 v[74:77], v[160:163], v[230:233], v[74:77]
	v_mfma_f32_16x16x32_bf16 v[70:73], v[182:185], v[226:229], v[70:73]
	v_mfma_f32_16x16x32_bf16 v[70:73], v[186:189], v[230:233], v[70:73]
	s_barrier
	ds_read_b128 v[190:193], v142 offset:49152
	ds_read_b128 v[194:197], v142 offset:50176
	ds_read_b128 v[198:201], v142 offset:51200
	ds_read_b128 v[214:217], v142 offset:52224
	ds_read_b128 v[218:221], v142 offset:53248
	ds_read_b128 v[222:225], v142 offset:54272
	ds_read_b128 v[226:229], v142 offset:55296
	ds_read_b128 v[230:233], v142 offset:56320
	s_add_i32 m0, s14, 0x18000
	v_lshl_add_u64 v[236:237], v[202:203], 0, s[34:35]
	global_load_lds_dwordx4 v[236:237], off
	s_add_i32 m0, s14, 0x1a000
	v_lshl_add_u64 v[236:237], v[202:203], 0, s[38:39]
	global_load_lds_dwordx4 v[236:237], off
	v_lshl_add_u64 v[236:237], v[202:203], 0, s[44:45]
	s_add_i32 m0, s14, 0x1c000
	v_lshl_add_u64 v[202:203], v[202:203], 0, s[10:11]
	global_load_lds_dwordx4 v[236:237], off
	s_add_i32 m0, s14, 0x1e000
	s_nop 0
	global_load_lds_dwordx4 v[202:203], off
	v_lshl_add_u64 v[202:203], v[234:235], 0, s[34:35]
	s_mov_b32 m0, s79
	s_nop 0
	global_load_lds_dwordx4 v[202:203], off
	v_lshl_add_u64 v[202:203], v[234:235], 0, s[38:39]
	s_mov_b32 m0, s88
	s_nop 0
	global_load_lds_dwordx4 v[202:203], off
	s_waitcnt vmcnt(8) lgkmcnt(0)
	s_barrier
	v_mfma_f32_16x16x32_bf16 v[62:65], v[134:137], v[190:193], v[62:65]
	v_mfma_f32_16x16x32_bf16 v[62:65], v[144:147], v[194:197], v[62:65]
	v_mfma_f32_16x16x32_bf16 v[50:53], v[148:151], v[190:193], v[50:53]
	v_mfma_f32_16x16x32_bf16 v[50:53], v[152:155], v[194:197], v[50:53]
	v_mfma_f32_16x16x32_bf16 v[46:49], v[134:137], v[198:201], v[46:49]
	v_mfma_f32_16x16x32_bf16 v[46:49], v[144:147], v[214:217], v[46:49]
	v_mfma_f32_16x16x32_bf16 v[34:37], v[148:151], v[198:201], v[34:37]
	v_mfma_f32_16x16x32_bf16 v[34:37], v[152:155], v[214:217], v[34:37]
	v_mfma_f32_16x16x32_bf16 v[30:33], v[134:137], v[218:221], v[30:33]
	v_mfma_f32_16x16x32_bf16 v[30:33], v[144:147], v[222:225], v[30:33]
	v_mfma_f32_16x16x32_bf16 v[18:21], v[148:151], v[218:221], v[18:21]
	v_mfma_f32_16x16x32_bf16 v[18:21], v[152:155], v[222:225], v[18:21]
	v_mfma_f32_16x16x32_bf16 v[14:17], v[134:137], v[226:229], v[14:17]
	v_mfma_f32_16x16x32_bf16 v[14:17], v[144:147], v[230:233], v[14:17]
	v_mfma_f32_16x16x32_bf16 v[6:9], v[148:151], v[226:229], v[6:9]
	v_mfma_f32_16x16x32_bf16 v[6:9], v[152:155], v[230:233], v[6:9]
	s_add_i32 s97, s97, 2
	s_add_u32 s68, s68, 0x100
	s_addc_u32 s69, s69, 0
	s_add_u32 s91, s91, 0x100
	s_addc_u32 s96, s96, 0
	v_mfma_f32_16x16x32_bf16 v[58:61], v[156:159], v[190:193], v[58:61]
	v_mfma_f32_16x16x32_bf16 v[58:61], v[160:163], v[194:197], v[58:61]
	v_mfma_f32_16x16x32_bf16 v[54:57], v[182:185], v[190:193], v[54:57]
	v_mfma_f32_16x16x32_bf16 v[54:57], v[186:189], v[194:197], v[54:57]
	v_mfma_f32_16x16x32_bf16 v[42:45], v[156:159], v[198:201], v[42:45]
	v_mfma_f32_16x16x32_bf16 v[42:45], v[160:163], v[214:217], v[42:45]
	v_mfma_f32_16x16x32_bf16 v[38:41], v[182:185], v[198:201], v[38:41]
	v_mfma_f32_16x16x32_bf16 v[38:41], v[186:189], v[214:217], v[38:41]
	v_mfma_f32_16x16x32_bf16 v[26:29], v[156:159], v[218:221], v[26:29]
	v_mfma_f32_16x16x32_bf16 v[26:29], v[160:163], v[222:225], v[26:29]
	v_mfma_f32_16x16x32_bf16 v[22:25], v[182:185], v[218:221], v[22:25]
	v_mfma_f32_16x16x32_bf16 v[22:25], v[186:189], v[222:225], v[22:25]
	v_mfma_f32_16x16x32_bf16 v[10:13], v[156:159], v[226:229], v[10:13]
	v_mfma_f32_16x16x32_bf16 v[10:13], v[160:163], v[230:233], v[10:13]
	v_mfma_f32_16x16x32_bf16 v[2:5], v[182:185], v[226:229], v[2:5]
	v_mfma_f32_16x16x32_bf16 v[2:5], v[186:189], v[230:233], v[2:5]
	s_barrier
	s_branch .LBB0_488
	.p2alignl 6, 3212836864
.LBB0_488:
	ds_read_b128 v[134:137], v243
	ds_read_b128 v[144:147], v243 offset:1024
	ds_read_b128 v[148:151], v243 offset:2048
	ds_read_b128 v[152:155], v243 offset:3072
	ds_read_b128 v[156:159], v243 offset:16384
	ds_read_b128 v[160:163], v243 offset:17408
	ds_read_b128 v[182:185], v243 offset:18432
	ds_read_b128 v[186:189], v243 offset:19456
	ds_read_b128 v[190:193], v142
	ds_read_b128 v[194:197], v142 offset:1024
	ds_read_b128 v[198:201], v142 offset:2048
	ds_read_b128 v[214:217], v142 offset:3072
	ds_read_b128 v[218:221], v142 offset:4096
	ds_read_b128 v[222:225], v142 offset:5120
	ds_read_b128 v[226:229], v142 offset:6144
	ds_read_b128 v[230:233], v142 offset:7168
	s_add_u32 s20, s68, 0xfffc0080
	s_addc_u32 s21, s69, -1
	s_cmp_eq_u32 s97, 12
	s_cselect_b32 s77, s57, s21
	s_cselect_b32 s76, s86, s20
	s_cselect_b32 s21, s51, s96
	s_cselect_b32 s20, s87, s91
	s_add_i32 m0, s43, 0xc000
	v_lshl_add_u64 v[202:203], s[68:69], 0, v[132:133]
	global_load_lds_dwordx4 v[202:203], off
	s_add_i32 m0, s43, 0xe000
	v_lshl_add_u64 v[202:203], v[202:203], 0, s[72:73]
	global_load_lds_dwordx4 v[202:203], off
	s_waitcnt vmcnt(8) lgkmcnt(0)
	s_barrier
	v_mfma_f32_16x16x32_bf16 v[126:129], v[134:137], v[190:193], v[126:129]
	v_mfma_f32_16x16x32_bf16 v[126:129], v[144:147], v[194:197], v[126:129]
	v_mfma_f32_16x16x32_bf16 v[114:117], v[148:151], v[190:193], v[114:117]
	v_mfma_f32_16x16x32_bf16 v[114:117], v[152:155], v[194:197], v[114:117]
	v_mfma_f32_16x16x32_bf16 v[110:113], v[134:137], v[198:201], v[110:113]
	v_mfma_f32_16x16x32_bf16 v[110:113], v[144:147], v[214:217], v[110:113]
	v_mfma_f32_16x16x32_bf16 v[98:101], v[148:151], v[198:201], v[98:101]
	v_mfma_f32_16x16x32_bf16 v[98:101], v[152:155], v[214:217], v[98:101]
	v_mfma_f32_16x16x32_bf16 v[94:97], v[134:137], v[218:221], v[94:97]
	v_mfma_f32_16x16x32_bf16 v[94:97], v[144:147], v[222:225], v[94:97]
	v_mfma_f32_16x16x32_bf16 v[82:85], v[148:151], v[218:221], v[82:85]
	v_mfma_f32_16x16x32_bf16 v[82:85], v[152:155], v[222:225], v[82:85]
	v_mfma_f32_16x16x32_bf16 v[78:81], v[134:137], v[226:229], v[78:81]
	v_mfma_f32_16x16x32_bf16 v[78:81], v[144:147], v[230:233], v[78:81]
	v_mfma_f32_16x16x32_bf16 v[66:69], v[148:151], v[226:229], v[66:69]
	v_mfma_f32_16x16x32_bf16 v[66:69], v[152:155], v[230:233], v[66:69]
	v_mfma_f32_16x16x32_bf16 v[122:125], v[156:159], v[190:193], v[122:125]
	v_mfma_f32_16x16x32_bf16 v[122:125], v[160:163], v[194:197], v[122:125]
	v_mfma_f32_16x16x32_bf16 v[118:121], v[182:185], v[190:193], v[118:121]
	v_mfma_f32_16x16x32_bf16 v[118:121], v[186:189], v[194:197], v[118:121]
	v_mfma_f32_16x16x32_bf16 v[106:109], v[156:159], v[198:201], v[106:109]
	v_mfma_f32_16x16x32_bf16 v[106:109], v[160:163], v[214:217], v[106:109]
	v_mfma_f32_16x16x32_bf16 v[102:105], v[182:185], v[198:201], v[102:105]
	v_mfma_f32_16x16x32_bf16 v[102:105], v[186:189], v[214:217], v[102:105]
	v_mfma_f32_16x16x32_bf16 v[90:93], v[156:159], v[218:221], v[90:93]
	v_mfma_f32_16x16x32_bf16 v[90:93], v[160:163], v[222:225], v[90:93]
	v_mfma_f32_16x16x32_bf16 v[86:89], v[182:185], v[218:221], v[86:89]
	v_mfma_f32_16x16x32_bf16 v[86:89], v[186:189], v[222:225], v[86:89]
	v_mfma_f32_16x16x32_bf16 v[74:77], v[156:159], v[226:229], v[74:77]
	v_mfma_f32_16x16x32_bf16 v[74:77], v[160:163], v[230:233], v[74:77]
	v_mfma_f32_16x16x32_bf16 v[70:73], v[182:185], v[226:229], v[70:73]
	v_mfma_f32_16x16x32_bf16 v[70:73], v[186:189], v[230:233], v[70:73]
	s_barrier
	ds_read_b128 v[190:193], v142 offset:16384
	ds_read_b128 v[194:197], v142 offset:17408
	ds_read_b128 v[198:201], v142 offset:18432
	ds_read_b128 v[214:217], v142 offset:19456
	ds_read_b128 v[218:221], v142 offset:20480
	ds_read_b128 v[222:225], v142 offset:21504
	ds_read_b128 v[226:229], v142 offset:22528
	ds_read_b128 v[230:233], v142 offset:23552
	s_add_i32 m0, s14, 0x10000
	v_lshl_add_u64 v[202:203], s[20:21], 0, v[0:1]
	global_load_lds_dwordx4 v[202:203], off
	s_add_i32 m0, s14, 0x12000
	v_lshl_add_u64 v[234:235], v[202:203], 0, s[72:73]
	global_load_lds_dwordx4 v[234:235], off
	s_add_i32 m0, s14, 0x14000
	v_lshl_add_u64 v[234:235], v[202:203], 0, s[28:29]
	global_load_lds_dwordx4 v[234:235], off
	s_add_i32 m0, s14, 0x16000
	v_lshl_add_u64 v[234:235], v[202:203], 0, s[82:83]
	global_load_lds_dwordx4 v[234:235], off
	v_lshl_add_u64 v[234:235], s[76:77], 0, v[130:131]
	s_mov_b32 m0, s43
	v_lshl_add_u64 v[236:237], v[234:235], 0, s[72:73]
	global_load_lds_dwordx4 v[234:235], off
	s_mov_b32 m0, s46
	s_nop 0
	global_load_lds_dwordx4 v[236:237], off
	s_waitcnt vmcnt(8) lgkmcnt(0)
	s_barrier
	v_mfma_f32_16x16x32_bf16 v[62:65], v[134:137], v[190:193], v[62:65]
	v_mfma_f32_16x16x32_bf16 v[62:65], v[144:147], v[194:197], v[62:65]
	v_mfma_f32_16x16x32_bf16 v[50:53], v[148:151], v[190:193], v[50:53]
	v_mfma_f32_16x16x32_bf16 v[50:53], v[152:155], v[194:197], v[50:53]
	v_mfma_f32_16x16x32_bf16 v[46:49], v[134:137], v[198:201], v[46:49]
	v_mfma_f32_16x16x32_bf16 v[46:49], v[144:147], v[214:217], v[46:49]
	v_mfma_f32_16x16x32_bf16 v[34:37], v[148:151], v[198:201], v[34:37]
	v_mfma_f32_16x16x32_bf16 v[34:37], v[152:155], v[214:217], v[34:37]
	v_mfma_f32_16x16x32_bf16 v[30:33], v[134:137], v[218:221], v[30:33]
	v_mfma_f32_16x16x32_bf16 v[30:33], v[144:147], v[222:225], v[30:33]
	v_mfma_f32_16x16x32_bf16 v[18:21], v[148:151], v[218:221], v[18:21]
	v_mfma_f32_16x16x32_bf16 v[18:21], v[152:155], v[222:225], v[18:21]
	v_mfma_f32_16x16x32_bf16 v[14:17], v[134:137], v[226:229], v[14:17]
	v_mfma_f32_16x16x32_bf16 v[14:17], v[144:147], v[230:233], v[14:17]
	v_mfma_f32_16x16x32_bf16 v[6:9], v[148:151], v[226:229], v[6:9]
	v_mfma_f32_16x16x32_bf16 v[6:9], v[152:155], v[230:233], v[6:9]
	v_mfma_f32_16x16x32_bf16 v[58:61], v[156:159], v[190:193], v[58:61]
	v_mfma_f32_16x16x32_bf16 v[58:61], v[160:163], v[194:197], v[58:61]
	v_mfma_f32_16x16x32_bf16 v[54:57], v[182:185], v[190:193], v[54:57]
	v_mfma_f32_16x16x32_bf16 v[54:57], v[186:189], v[194:197], v[54:57]
	v_mfma_f32_16x16x32_bf16 v[42:45], v[156:159], v[198:201], v[42:45]
	v_mfma_f32_16x16x32_bf16 v[42:45], v[160:163], v[214:217], v[42:45]
	v_mfma_f32_16x16x32_bf16 v[38:41], v[182:185], v[198:201], v[38:41]
	v_mfma_f32_16x16x32_bf16 v[38:41], v[186:189], v[214:217], v[38:41]
	v_mfma_f32_16x16x32_bf16 v[26:29], v[156:159], v[218:221], v[26:29]
	v_mfma_f32_16x16x32_bf16 v[26:29], v[160:163], v[222:225], v[26:29]
	v_mfma_f32_16x16x32_bf16 v[22:25], v[182:185], v[218:221], v[22:25]
	v_mfma_f32_16x16x32_bf16 v[22:25], v[186:189], v[222:225], v[22:25]
	v_mfma_f32_16x16x32_bf16 v[10:13], v[156:159], v[226:229], v[10:13]
	v_mfma_f32_16x16x32_bf16 v[10:13], v[160:163], v[230:233], v[10:13]
	v_mfma_f32_16x16x32_bf16 v[2:5], v[182:185], v[226:229], v[2:5]
	v_mfma_f32_16x16x32_bf16 v[2:5], v[186:189], v[230:233], v[2:5]
	s_barrier
	ds_read_b128 v[134:137], v243 offset:32768
	ds_read_b128 v[144:147], v243 offset:33792
	ds_read_b128 v[148:151], v243 offset:34816
	ds_read_b128 v[152:155], v243 offset:35840
	ds_read_b128 v[156:159], v243 offset:49152
	ds_read_b128 v[160:163], v243 offset:50176
	ds_read_b128 v[182:185], v243 offset:51200
	ds_read_b128 v[186:189], v243 offset:52224
	ds_read_b128 v[190:193], v142 offset:32768
	ds_read_b128 v[194:197], v142 offset:33792
	ds_read_b128 v[198:201], v142 offset:34816
	ds_read_b128 v[214:217], v142 offset:35840
	ds_read_b128 v[218:221], v142 offset:36864
	ds_read_b128 v[222:225], v142 offset:37888
	ds_read_b128 v[226:229], v142 offset:38912
	ds_read_b128 v[230:233], v142 offset:39936
	s_mov_b32 m0, s47
	v_lshl_add_u64 v[236:237], v[234:235], 0, s[28:29]
	global_load_lds_dwordx4 v[236:237], off
	v_lshl_add_u64 v[236:237], v[234:235], 0, s[82:83]
	s_mov_b32 m0, s78
	s_nop 0
	global_load_lds_dwordx4 v[236:237], off
	s_waitcnt vmcnt(8) lgkmcnt(0)
	s_barrier
	v_mfma_f32_16x16x32_bf16 v[126:129], v[134:137], v[190:193], v[126:129]
	v_mfma_f32_16x16x32_bf16 v[126:129], v[144:147], v[194:197], v[126:129]
	v_mfma_f32_16x16x32_bf16 v[114:117], v[148:151], v[190:193], v[114:117]
	v_mfma_f32_16x16x32_bf16 v[114:117], v[152:155], v[194:197], v[114:117]
	v_mfma_f32_16x16x32_bf16 v[110:113], v[134:137], v[198:201], v[110:113]
	v_mfma_f32_16x16x32_bf16 v[110:113], v[144:147], v[214:217], v[110:113]
	v_mfma_f32_16x16x32_bf16 v[98:101], v[148:151], v[198:201], v[98:101]
	v_mfma_f32_16x16x32_bf16 v[98:101], v[152:155], v[214:217], v[98:101]
	v_mfma_f32_16x16x32_bf16 v[94:97], v[134:137], v[218:221], v[94:97]
	v_mfma_f32_16x16x32_bf16 v[94:97], v[144:147], v[222:225], v[94:97]
	v_mfma_f32_16x16x32_bf16 v[82:85], v[148:151], v[218:221], v[82:85]
	v_mfma_f32_16x16x32_bf16 v[82:85], v[152:155], v[222:225], v[82:85]
	v_mfma_f32_16x16x32_bf16 v[78:81], v[134:137], v[226:229], v[78:81]
	v_mfma_f32_16x16x32_bf16 v[78:81], v[144:147], v[230:233], v[78:81]
	v_mfma_f32_16x16x32_bf16 v[66:69], v[148:151], v[226:229], v[66:69]
	v_mfma_f32_16x16x32_bf16 v[66:69], v[152:155], v[230:233], v[66:69]
	v_mfma_f32_16x16x32_bf16 v[122:125], v[156:159], v[190:193], v[122:125]
	v_mfma_f32_16x16x32_bf16 v[122:125], v[160:163], v[194:197], v[122:125]
	v_mfma_f32_16x16x32_bf16 v[118:121], v[182:185], v[190:193], v[118:121]
	v_mfma_f32_16x16x32_bf16 v[118:121], v[186:189], v[194:197], v[118:121]
	v_mfma_f32_16x16x32_bf16 v[106:109], v[156:159], v[198:201], v[106:109]
	v_mfma_f32_16x16x32_bf16 v[106:109], v[160:163], v[214:217], v[106:109]
	v_mfma_f32_16x16x32_bf16 v[102:105], v[182:185], v[198:201], v[102:105]
	v_mfma_f32_16x16x32_bf16 v[102:105], v[186:189], v[214:217], v[102:105]
	v_mfma_f32_16x16x32_bf16 v[90:93], v[156:159], v[218:221], v[90:93]
	v_mfma_f32_16x16x32_bf16 v[90:93], v[160:163], v[222:225], v[90:93]
	v_mfma_f32_16x16x32_bf16 v[86:89], v[182:185], v[218:221], v[86:89]
	v_mfma_f32_16x16x32_bf16 v[86:89], v[186:189], v[222:225], v[86:89]
	v_mfma_f32_16x16x32_bf16 v[74:77], v[156:159], v[226:229], v[74:77]
	v_mfma_f32_16x16x32_bf16 v[74:77], v[160:163], v[230:233], v[74:77]
	v_mfma_f32_16x16x32_bf16 v[70:73], v[182:185], v[226:229], v[70:73]
	v_mfma_f32_16x16x32_bf16 v[70:73], v[186:189], v[230:233], v[70:73]
	s_barrier
	ds_read_b128 v[190:193], v142 offset:49152
	ds_read_b128 v[194:197], v142 offset:50176
	ds_read_b128 v[198:201], v142 offset:51200
	ds_read_b128 v[214:217], v142 offset:52224
	ds_read_b128 v[218:221], v142 offset:53248
	ds_read_b128 v[222:225], v142 offset:54272
	ds_read_b128 v[226:229], v142 offset:55296
	ds_read_b128 v[230:233], v142 offset:56320
	s_add_i32 m0, s14, 0x18000
	v_lshl_add_u64 v[236:237], v[202:203], 0, s[34:35]
	global_load_lds_dwordx4 v[236:237], off
	s_add_i32 m0, s14, 0x1a000
	v_lshl_add_u64 v[236:237], v[202:203], 0, s[38:39]
	global_load_lds_dwordx4 v[236:237], off
	v_lshl_add_u64 v[236:237], v[202:203], 0, s[44:45]
	s_add_i32 m0, s14, 0x1c000
	v_lshl_add_u64 v[202:203], v[202:203], 0, s[10:11]
	global_load_lds_dwordx4 v[236:237], off
	s_add_i32 m0, s14, 0x1e000
	s_nop 0
	global_load_lds_dwordx4 v[202:203], off
	v_lshl_add_u64 v[202:203], v[234:235], 0, s[34:35]
	s_mov_b32 m0, s79
	s_nop 0
	global_load_lds_dwordx4 v[202:203], off
	v_lshl_add_u64 v[202:203], v[234:235], 0, s[38:39]
	s_mov_b32 m0, s88
	s_nop 0
	global_load_lds_dwordx4 v[202:203], off
	s_waitcnt vmcnt(8) lgkmcnt(0)
	s_barrier
	v_mfma_f32_16x16x32_bf16 v[62:65], v[134:137], v[190:193], v[62:65]
	v_mfma_f32_16x16x32_bf16 v[62:65], v[144:147], v[194:197], v[62:65]
	v_mfma_f32_16x16x32_bf16 v[50:53], v[148:151], v[190:193], v[50:53]
	v_mfma_f32_16x16x32_bf16 v[50:53], v[152:155], v[194:197], v[50:53]
	v_mfma_f32_16x16x32_bf16 v[46:49], v[134:137], v[198:201], v[46:49]
	v_mfma_f32_16x16x32_bf16 v[46:49], v[144:147], v[214:217], v[46:49]
	v_mfma_f32_16x16x32_bf16 v[34:37], v[148:151], v[198:201], v[34:37]
	v_mfma_f32_16x16x32_bf16 v[34:37], v[152:155], v[214:217], v[34:37]
	v_mfma_f32_16x16x32_bf16 v[30:33], v[134:137], v[218:221], v[30:33]
	v_mfma_f32_16x16x32_bf16 v[30:33], v[144:147], v[222:225], v[30:33]
	v_mfma_f32_16x16x32_bf16 v[18:21], v[148:151], v[218:221], v[18:21]
	v_mfma_f32_16x16x32_bf16 v[18:21], v[152:155], v[222:225], v[18:21]
	v_mfma_f32_16x16x32_bf16 v[14:17], v[134:137], v[226:229], v[14:17]
	v_mfma_f32_16x16x32_bf16 v[14:17], v[144:147], v[230:233], v[14:17]
	v_mfma_f32_16x16x32_bf16 v[6:9], v[148:151], v[226:229], v[6:9]
	v_mfma_f32_16x16x32_bf16 v[6:9], v[152:155], v[230:233], v[6:9]
	s_add_i32 s97, s97, 2
	s_add_u32 s68, s68, 0x100
	s_addc_u32 s69, s69, 0
	s_add_u32 s91, s91, 0x100
	s_addc_u32 s96, s96, 0
	v_mfma_f32_16x16x32_bf16 v[58:61], v[156:159], v[190:193], v[58:61]
	v_mfma_f32_16x16x32_bf16 v[58:61], v[160:163], v[194:197], v[58:61]
	v_mfma_f32_16x16x32_bf16 v[54:57], v[182:185], v[190:193], v[54:57]
	v_mfma_f32_16x16x32_bf16 v[54:57], v[186:189], v[194:197], v[54:57]
	v_mfma_f32_16x16x32_bf16 v[42:45], v[156:159], v[198:201], v[42:45]
	v_mfma_f32_16x16x32_bf16 v[42:45], v[160:163], v[214:217], v[42:45]
	v_mfma_f32_16x16x32_bf16 v[38:41], v[182:185], v[198:201], v[38:41]
	v_mfma_f32_16x16x32_bf16 v[38:41], v[186:189], v[214:217], v[38:41]
	v_mfma_f32_16x16x32_bf16 v[26:29], v[156:159], v[218:221], v[26:29]
	v_mfma_f32_16x16x32_bf16 v[26:29], v[160:163], v[222:225], v[26:29]
	v_mfma_f32_16x16x32_bf16 v[22:25], v[182:185], v[218:221], v[22:25]
	v_mfma_f32_16x16x32_bf16 v[22:25], v[186:189], v[222:225], v[22:25]
	v_mfma_f32_16x16x32_bf16 v[10:13], v[156:159], v[226:229], v[10:13]
	v_mfma_f32_16x16x32_bf16 v[10:13], v[160:163], v[230:233], v[10:13]
	v_mfma_f32_16x16x32_bf16 v[2:5], v[182:185], v[226:229], v[2:5]
	v_mfma_f32_16x16x32_bf16 v[2:5], v[186:189], v[230:233], v[2:5]
	s_barrier
	s_cmp_gt_u32 s97, 13
	s_cbranch_scc0 .LBB0_488
	s_setprio 0
	s_and_b64 vcc, exec, s[48:49]
	s_cbranch_vccz .LBB0_491
	s_barrier

.Lmid1_604:
	s_add_u32 s20, s6, 0xfffe0080
	s_addc_u32 s21, s7, -1
	s_cmp_eq_u32 s84, 4
	s_cselect_b32 s69, s42, s21
	s_cselect_b32 s68, s43, s20
	s_cselect_b32 s21, s46, s51
	s_cselect_b32 s20, s47, s49
	s_add_i32 m0, s89, 0xc000
	v_lshl_add_u64 v[162:163], s[6:7], 0, v[132:133]
	global_load_lds_dwordx4 v[162:163], off
	s_add_i32 m0, s89, 0xe000
	v_lshl_add_u64 v[162:163], v[162:163], 0, s[64:65]
	global_load_lds_dwordx4 v[162:163], off
	s_waitcnt vmcnt(8) lgkmcnt(0)
	s_barrier
	v_mfma_f32_16x16x32_bf16 v[126:129], v[134:137], v[190:193], 0
	v_mfma_f32_16x16x32_bf16 v[126:129], v[142:145], v[194:197], v[126:129]
	v_mfma_f32_16x16x32_bf16 v[122:125], v[146:149], v[190:193], 0
	v_mfma_f32_16x16x32_bf16 v[122:125], v[150:153], v[194:197], v[122:125]
	v_mfma_f32_16x16x32_bf16 v[110:113], v[134:137], v[198:201], 0
	v_mfma_f32_16x16x32_bf16 v[110:113], v[142:145], v[214:217], v[110:113]
	v_mfma_f32_16x16x32_bf16 v[106:109], v[146:149], v[198:201], 0
	v_mfma_f32_16x16x32_bf16 v[106:109], v[150:153], v[214:217], v[106:109]
	v_mfma_f32_16x16x32_bf16 v[94:97], v[134:137], v[218:221], 0
	v_mfma_f32_16x16x32_bf16 v[94:97], v[142:145], v[222:225], v[94:97]
	v_mfma_f32_16x16x32_bf16 v[90:93], v[146:149], v[218:221], 0
	v_mfma_f32_16x16x32_bf16 v[90:93], v[150:153], v[222:225], v[90:93]
	v_mfma_f32_16x16x32_bf16 v[78:81], v[134:137], v[226:229], 0
	v_mfma_f32_16x16x32_bf16 v[78:81], v[142:145], v[230:233], v[78:81]
	v_mfma_f32_16x16x32_bf16 v[74:77], v[146:149], v[226:229], 0
	v_mfma_f32_16x16x32_bf16 v[74:77], v[150:153], v[230:233], v[74:77]
	v_mfma_f32_16x16x32_bf16 v[118:121], v[154:157], v[190:193], 0
	v_mfma_f32_16x16x32_bf16 v[118:121], v[158:161], v[194:197], v[118:121]
	v_mfma_f32_16x16x32_bf16 v[114:117], v[182:185], v[190:193], 0
	v_mfma_f32_16x16x32_bf16 v[114:117], v[186:189], v[194:197], v[114:117]
	v_mfma_f32_16x16x32_bf16 v[102:105], v[154:157], v[198:201], 0
	v_mfma_f32_16x16x32_bf16 v[102:105], v[158:161], v[214:217], v[102:105]
	v_mfma_f32_16x16x32_bf16 v[98:101], v[182:185], v[198:201], 0
	v_mfma_f32_16x16x32_bf16 v[98:101], v[186:189], v[214:217], v[98:101]
	v_mfma_f32_16x16x32_bf16 v[86:89], v[154:157], v[218:221], 0
	v_mfma_f32_16x16x32_bf16 v[86:89], v[158:161], v[222:225], v[86:89]
	v_mfma_f32_16x16x32_bf16 v[82:85], v[182:185], v[218:221], 0
	v_mfma_f32_16x16x32_bf16 v[82:85], v[186:189], v[222:225], v[82:85]
	v_mfma_f32_16x16x32_bf16 v[70:73], v[154:157], v[226:229], 0
	v_mfma_f32_16x16x32_bf16 v[70:73], v[158:161], v[230:233], v[70:73]
	v_mfma_f32_16x16x32_bf16 v[66:69], v[182:185], v[226:229], 0
	v_mfma_f32_16x16x32_bf16 v[66:69], v[186:189], v[230:233], v[66:69]
	s_barrier
	ds_read_b128 v[190:193], v141 offset:16384
	ds_read_b128 v[194:197], v141 offset:17408
	ds_read_b128 v[198:201], v141 offset:18432
	ds_read_b128 v[214:217], v141 offset:19456
	ds_read_b128 v[218:221], v141 offset:20480
	ds_read_b128 v[222:225], v141 offset:21504
	ds_read_b128 v[226:229], v141 offset:22528
	ds_read_b128 v[230:233], v141 offset:23552
	s_add_i32 m0, s88, 0x10000
	v_lshl_add_u64 v[162:163], s[20:21], 0, v[0:1]
	global_load_lds_dwordx4 v[162:163], off
	s_add_i32 m0, s88, 0x12000
	v_lshl_add_u64 v[202:203], v[162:163], 0, s[64:65]
	global_load_lds_dwordx4 v[202:203], off
	s_add_i32 m0, s88, 0x14000
	v_lshl_add_u64 v[202:203], v[162:163], 0, s[72:73]
	global_load_lds_dwordx4 v[202:203], off
	s_add_i32 m0, s88, 0x16000
	v_lshl_add_u64 v[202:203], v[162:163], 0, s[74:75]
	global_load_lds_dwordx4 v[202:203], off
	v_lshl_add_u64 v[202:203], s[68:69], 0, v[130:131]
	s_mov_b32 m0, s89
	v_lshl_add_u64 v[234:235], v[202:203], 0, s[64:65]
	global_load_lds_dwordx4 v[202:203], off
	s_mov_b32 m0, s90
	s_nop 0
	global_load_lds_dwordx4 v[234:235], off
	s_waitcnt vmcnt(8) lgkmcnt(0)
	s_barrier
	v_mfma_f32_16x16x32_bf16 v[62:65], v[134:137], v[190:193], 0
	v_mfma_f32_16x16x32_bf16 v[62:65], v[142:145], v[194:197], v[62:65]
	v_mfma_f32_16x16x32_bf16 v[58:61], v[146:149], v[190:193], 0
	v_mfma_f32_16x16x32_bf16 v[58:61], v[150:153], v[194:197], v[58:61]
	v_mfma_f32_16x16x32_bf16 v[46:49], v[134:137], v[198:201], 0
	v_mfma_f32_16x16x32_bf16 v[46:49], v[142:145], v[214:217], v[46:49]
	v_mfma_f32_16x16x32_bf16 v[42:45], v[146:149], v[198:201], 0
	v_mfma_f32_16x16x32_bf16 v[42:45], v[150:153], v[214:217], v[42:45]
	v_mfma_f32_16x16x32_bf16 v[30:33], v[134:137], v[218:221], 0
	v_mfma_f32_16x16x32_bf16 v[30:33], v[142:145], v[222:225], v[30:33]
	v_mfma_f32_16x16x32_bf16 v[26:29], v[146:149], v[218:221], 0
	v_mfma_f32_16x16x32_bf16 v[26:29], v[150:153], v[222:225], v[26:29]
	v_mfma_f32_16x16x32_bf16 v[14:17], v[134:137], v[226:229], 0
	v_mfma_f32_16x16x32_bf16 v[14:17], v[142:145], v[230:233], v[14:17]
	v_mfma_f32_16x16x32_bf16 v[10:13], v[146:149], v[226:229], 0
	v_mfma_f32_16x16x32_bf16 v[10:13], v[150:153], v[230:233], v[10:13]
	v_mfma_f32_16x16x32_bf16 v[54:57], v[154:157], v[190:193], 0
	v_mfma_f32_16x16x32_bf16 v[54:57], v[158:161], v[194:197], v[54:57]
	v_mfma_f32_16x16x32_bf16 v[50:53], v[182:185], v[190:193], 0
	v_mfma_f32_16x16x32_bf16 v[50:53], v[186:189], v[194:197], v[50:53]
	v_mfma_f32_16x16x32_bf16 v[38:41], v[154:157], v[198:201], 0
	v_mfma_f32_16x16x32_bf16 v[38:41], v[158:161], v[214:217], v[38:41]
	v_mfma_f32_16x16x32_bf16 v[34:37], v[182:185], v[198:201], 0
	v_mfma_f32_16x16x32_bf16 v[34:37], v[186:189], v[214:217], v[34:37]
	v_mfma_f32_16x16x32_bf16 v[22:25], v[154:157], v[218:221], 0
	v_mfma_f32_16x16x32_bf16 v[22:25], v[158:161], v[222:225], v[22:25]
	v_mfma_f32_16x16x32_bf16 v[18:21], v[182:185], v[218:221], 0
	v_mfma_f32_16x16x32_bf16 v[18:21], v[186:189], v[222:225], v[18:21]
	v_mfma_f32_16x16x32_bf16 v[6:9], v[154:157], v[226:229], 0
	v_mfma_f32_16x16x32_bf16 v[6:9], v[158:161], v[230:233], v[6:9]
	v_mfma_f32_16x16x32_bf16 v[2:5], v[182:185], v[226:229], 0
	v_mfma_f32_16x16x32_bf16 v[2:5], v[186:189], v[230:233], v[2:5]
	s_barrier
	ds_read_b128 v[134:137], v243 offset:32768
	ds_read_b128 v[142:145], v243 offset:33792
	ds_read_b128 v[146:149], v243 offset:34816
	ds_read_b128 v[150:153], v243 offset:35840
	ds_read_b128 v[154:157], v243 offset:49152
	ds_read_b128 v[158:161], v243 offset:50176
	ds_read_b128 v[182:185], v243 offset:51200
	ds_read_b128 v[186:189], v243 offset:52224
	ds_read_b128 v[190:193], v141 offset:32768
	ds_read_b128 v[194:197], v141 offset:33792
	ds_read_b128 v[198:201], v141 offset:34816
	ds_read_b128 v[214:217], v141 offset:35840
	ds_read_b128 v[218:221], v141 offset:36864
	ds_read_b128 v[222:225], v141 offset:37888
	ds_read_b128 v[226:229], v141 offset:38912
	ds_read_b128 v[230:233], v141 offset:39936
	s_mov_b32 m0, s91
	v_lshl_add_u64 v[234:235], v[202:203], 0, s[72:73]
	global_load_lds_dwordx4 v[234:235], off
	v_lshl_add_u64 v[234:235], v[202:203], 0, s[74:75]
	s_mov_b32 m0, s96
	s_nop 0
	global_load_lds_dwordx4 v[234:235], off
	s_waitcnt vmcnt(8) lgkmcnt(0)
	s_barrier
	v_mfma_f32_16x16x32_bf16 v[126:129], v[134:137], v[190:193], v[126:129]
	v_mfma_f32_16x16x32_bf16 v[126:129], v[142:145], v[194:197], v[126:129]
	v_mfma_f32_16x16x32_bf16 v[122:125], v[146:149], v[190:193], v[122:125]
	v_mfma_f32_16x16x32_bf16 v[122:125], v[150:153], v[194:197], v[122:125]
	v_mfma_f32_16x16x32_bf16 v[110:113], v[134:137], v[198:201], v[110:113]
	v_mfma_f32_16x16x32_bf16 v[110:113], v[142:145], v[214:217], v[110:113]
	v_mfma_f32_16x16x32_bf16 v[106:109], v[146:149], v[198:201], v[106:109]
	v_mfma_f32_16x16x32_bf16 v[106:109], v[150:153], v[214:217], v[106:109]
	v_mfma_f32_16x16x32_bf16 v[94:97], v[134:137], v[218:221], v[94:97]
	v_mfma_f32_16x16x32_bf16 v[94:97], v[142:145], v[222:225], v[94:97]
	v_mfma_f32_16x16x32_bf16 v[90:93], v[146:149], v[218:221], v[90:93]
	v_mfma_f32_16x16x32_bf16 v[90:93], v[150:153], v[222:225], v[90:93]
	v_mfma_f32_16x16x32_bf16 v[78:81], v[134:137], v[226:229], v[78:81]
	v_mfma_f32_16x16x32_bf16 v[78:81], v[142:145], v[230:233], v[78:81]
	v_mfma_f32_16x16x32_bf16 v[74:77], v[146:149], v[226:229], v[74:77]
	v_mfma_f32_16x16x32_bf16 v[74:77], v[150:153], v[230:233], v[74:77]
	v_mfma_f32_16x16x32_bf16 v[118:121], v[154:157], v[190:193], v[118:121]
	v_mfma_f32_16x16x32_bf16 v[118:121], v[158:161], v[194:197], v[118:121]
	v_mfma_f32_16x16x32_bf16 v[114:117], v[182:185], v[190:193], v[114:117]
	v_mfma_f32_16x16x32_bf16 v[114:117], v[186:189], v[194:197], v[114:117]
	v_mfma_f32_16x16x32_bf16 v[102:105], v[154:157], v[198:201], v[102:105]
	v_mfma_f32_16x16x32_bf16 v[102:105], v[158:161], v[214:217], v[102:105]
	v_mfma_f32_16x16x32_bf16 v[98:101], v[182:185], v[198:201], v[98:101]
	v_mfma_f32_16x16x32_bf16 v[98:101], v[186:189], v[214:217], v[98:101]
	v_mfma_f32_16x16x32_bf16 v[86:89], v[154:157], v[218:221], v[86:89]
	v_mfma_f32_16x16x32_bf16 v[86:89], v[158:161], v[222:225], v[86:89]
	v_mfma_f32_16x16x32_bf16 v[82:85], v[182:185], v[218:221], v[82:85]
	v_mfma_f32_16x16x32_bf16 v[82:85], v[186:189], v[222:225], v[82:85]
	v_mfma_f32_16x16x32_bf16 v[70:73], v[154:157], v[226:229], v[70:73]
	v_mfma_f32_16x16x32_bf16 v[70:73], v[158:161], v[230:233], v[70:73]
	v_mfma_f32_16x16x32_bf16 v[66:69], v[182:185], v[226:229], v[66:69]
	v_mfma_f32_16x16x32_bf16 v[66:69], v[186:189], v[230:233], v[66:69]
	s_barrier
	ds_read_b128 v[190:193], v141 offset:49152
	ds_read_b128 v[194:197], v141 offset:50176
	ds_read_b128 v[198:201], v141 offset:51200
	ds_read_b128 v[214:217], v141 offset:52224
	ds_read_b128 v[218:221], v141 offset:53248
	ds_read_b128 v[222:225], v141 offset:54272
	ds_read_b128 v[226:229], v141 offset:55296
	ds_read_b128 v[230:233], v141 offset:56320
	s_add_i32 m0, s88, 0x18000
	v_lshl_add_u64 v[234:235], v[162:163], 0, s[34:35]
	global_load_lds_dwordx4 v[234:235], off
	s_add_i32 m0, s88, 0x1a000
	v_lshl_add_u64 v[234:235], v[162:163], 0, s[80:81]
	global_load_lds_dwordx4 v[234:235], off
	v_lshl_add_u64 v[234:235], v[162:163], 0, s[38:39]
	s_add_i32 m0, s88, 0x1c000
	v_lshl_add_u64 v[162:163], v[162:163], 0, s[86:87]
	global_load_lds_dwordx4 v[234:235], off
	s_add_i32 m0, s88, 0x1e000
	s_nop 0
	global_load_lds_dwordx4 v[162:163], off
	v_lshl_add_u64 v[162:163], v[202:203], 0, s[34:35]
	s_mov_b32 m0, s97
	s_nop 0
	global_load_lds_dwordx4 v[162:163], off
	v_lshl_add_u64 v[162:163], v[202:203], 0, s[80:81]
	s_mov_b32 m0, s58
	s_nop 0
	global_load_lds_dwordx4 v[162:163], off
	s_waitcnt vmcnt(8) lgkmcnt(0)
	s_barrier
	v_mfma_f32_16x16x32_bf16 v[62:65], v[134:137], v[190:193], v[62:65]
	v_mfma_f32_16x16x32_bf16 v[62:65], v[142:145], v[194:197], v[62:65]
	v_mfma_f32_16x16x32_bf16 v[58:61], v[146:149], v[190:193], v[58:61]
	v_mfma_f32_16x16x32_bf16 v[58:61], v[150:153], v[194:197], v[58:61]
	v_mfma_f32_16x16x32_bf16 v[46:49], v[134:137], v[198:201], v[46:49]
	v_mfma_f32_16x16x32_bf16 v[46:49], v[142:145], v[214:217], v[46:49]
	v_mfma_f32_16x16x32_bf16 v[42:45], v[146:149], v[198:201], v[42:45]
	v_mfma_f32_16x16x32_bf16 v[42:45], v[150:153], v[214:217], v[42:45]
	v_mfma_f32_16x16x32_bf16 v[30:33], v[134:137], v[218:221], v[30:33]
	v_mfma_f32_16x16x32_bf16 v[30:33], v[142:145], v[222:225], v[30:33]
	v_mfma_f32_16x16x32_bf16 v[26:29], v[146:149], v[218:221], v[26:29]
	v_mfma_f32_16x16x32_bf16 v[26:29], v[150:153], v[222:225], v[26:29]
	v_mfma_f32_16x16x32_bf16 v[14:17], v[134:137], v[226:229], v[14:17]
	v_mfma_f32_16x16x32_bf16 v[14:17], v[142:145], v[230:233], v[14:17]
	v_mfma_f32_16x16x32_bf16 v[10:13], v[146:149], v[226:229], v[10:13]
	v_mfma_f32_16x16x32_bf16 v[10:13], v[150:153], v[230:233], v[10:13]
	s_add_i32 s84, s84, 2
	s_add_u32 s6, s6, 0x100
	s_addc_u32 s7, s7, 0
	s_add_u32 s49, s49, 0x100
	s_addc_u32 s51, s51, 0
	v_mfma_f32_16x16x32_bf16 v[54:57], v[154:157], v[190:193], v[54:57]
	v_mfma_f32_16x16x32_bf16 v[54:57], v[158:161], v[194:197], v[54:57]
	v_mfma_f32_16x16x32_bf16 v[50:53], v[182:185], v[190:193], v[50:53]
	v_mfma_f32_16x16x32_bf16 v[50:53], v[186:189], v[194:197], v[50:53]
	v_mfma_f32_16x16x32_bf16 v[38:41], v[154:157], v[198:201], v[38:41]
	v_mfma_f32_16x16x32_bf16 v[38:41], v[158:161], v[214:217], v[38:41]
	v_mfma_f32_16x16x32_bf16 v[34:37], v[182:185], v[198:201], v[34:37]
	v_mfma_f32_16x16x32_bf16 v[34:37], v[186:189], v[214:217], v[34:37]
	v_mfma_f32_16x16x32_bf16 v[22:25], v[154:157], v[218:221], v[22:25]
	v_mfma_f32_16x16x32_bf16 v[22:25], v[158:161], v[222:225], v[22:25]
	v_mfma_f32_16x16x32_bf16 v[18:21], v[182:185], v[218:221], v[18:21]
	v_mfma_f32_16x16x32_bf16 v[18:21], v[186:189], v[222:225], v[18:21]
	v_mfma_f32_16x16x32_bf16 v[6:9], v[154:157], v[226:229], v[6:9]
	v_mfma_f32_16x16x32_bf16 v[6:9], v[158:161], v[230:233], v[6:9]
	v_mfma_f32_16x16x32_bf16 v[2:5], v[182:185], v[226:229], v[2:5]
	v_mfma_f32_16x16x32_bf16 v[2:5], v[186:189], v[230:233], v[2:5]
	s_barrier
	s_branch .LBB0_604
	.p2alignl 6, 3212836864
.LBB0_604:
	ds_read_b128 v[134:137], v243
	ds_read_b128 v[142:145], v243 offset:1024
	ds_read_b128 v[146:149], v243 offset:2048
	ds_read_b128 v[150:153], v243 offset:3072
	ds_read_b128 v[154:157], v243 offset:16384
	ds_read_b128 v[158:161], v243 offset:17408
	ds_read_b128 v[182:185], v243 offset:18432
	ds_read_b128 v[186:189], v243 offset:19456
	ds_read_b128 v[190:193], v141
	ds_read_b128 v[194:197], v141 offset:1024
	ds_read_b128 v[198:201], v141 offset:2048
	ds_read_b128 v[214:217], v141 offset:3072
	ds_read_b128 v[218:221], v141 offset:4096
	ds_read_b128 v[222:225], v141 offset:5120
	ds_read_b128 v[226:229], v141 offset:6144
	ds_read_b128 v[230:233], v141 offset:7168
	s_add_u32 s20, s6, 0xfffe0080
	s_addc_u32 s21, s7, -1
	s_cmp_eq_u32 s84, 4
	s_cselect_b32 s69, s42, s21
	s_cselect_b32 s68, s43, s20
	s_cselect_b32 s21, s46, s51
	s_cselect_b32 s20, s47, s49
	s_add_i32 m0, s89, 0xc000
	v_lshl_add_u64 v[162:163], s[6:7], 0, v[132:133]
	global_load_lds_dwordx4 v[162:163], off
	s_add_i32 m0, s89, 0xe000
	v_lshl_add_u64 v[162:163], v[162:163], 0, s[64:65]
	global_load_lds_dwordx4 v[162:163], off
	s_waitcnt vmcnt(8) lgkmcnt(0)
	s_barrier
	v_mfma_f32_16x16x32_bf16 v[126:129], v[134:137], v[190:193], v[126:129]
	v_mfma_f32_16x16x32_bf16 v[126:129], v[142:145], v[194:197], v[126:129]
	v_mfma_f32_16x16x32_bf16 v[122:125], v[146:149], v[190:193], v[122:125]
	v_mfma_f32_16x16x32_bf16 v[122:125], v[150:153], v[194:197], v[122:125]
	v_mfma_f32_16x16x32_bf16 v[110:113], v[134:137], v[198:201], v[110:113]
	v_mfma_f32_16x16x32_bf16 v[110:113], v[142:145], v[214:217], v[110:113]
	v_mfma_f32_16x16x32_bf16 v[106:109], v[146:149], v[198:201], v[106:109]
	v_mfma_f32_16x16x32_bf16 v[106:109], v[150:153], v[214:217], v[106:109]
	v_mfma_f32_16x16x32_bf16 v[94:97], v[134:137], v[218:221], v[94:97]
	v_mfma_f32_16x16x32_bf16 v[94:97], v[142:145], v[222:225], v[94:97]
	v_mfma_f32_16x16x32_bf16 v[90:93], v[146:149], v[218:221], v[90:93]
	v_mfma_f32_16x16x32_bf16 v[90:93], v[150:153], v[222:225], v[90:93]
	v_mfma_f32_16x16x32_bf16 v[78:81], v[134:137], v[226:229], v[78:81]
	v_mfma_f32_16x16x32_bf16 v[78:81], v[142:145], v[230:233], v[78:81]
	v_mfma_f32_16x16x32_bf16 v[74:77], v[146:149], v[226:229], v[74:77]
	v_mfma_f32_16x16x32_bf16 v[74:77], v[150:153], v[230:233], v[74:77]
	v_mfma_f32_16x16x32_bf16 v[118:121], v[154:157], v[190:193], v[118:121]
	v_mfma_f32_16x16x32_bf16 v[118:121], v[158:161], v[194:197], v[118:121]
	v_mfma_f32_16x16x32_bf16 v[114:117], v[182:185], v[190:193], v[114:117]
	v_mfma_f32_16x16x32_bf16 v[114:117], v[186:189], v[194:197], v[114:117]
	v_mfma_f32_16x16x32_bf16 v[102:105], v[154:157], v[198:201], v[102:105]
	v_mfma_f32_16x16x32_bf16 v[102:105], v[158:161], v[214:217], v[102:105]
	v_mfma_f32_16x16x32_bf16 v[98:101], v[182:185], v[198:201], v[98:101]
	v_mfma_f32_16x16x32_bf16 v[98:101], v[186:189], v[214:217], v[98:101]
	v_mfma_f32_16x16x32_bf16 v[86:89], v[154:157], v[218:221], v[86:89]
	v_mfma_f32_16x16x32_bf16 v[86:89], v[158:161], v[222:225], v[86:89]
	v_mfma_f32_16x16x32_bf16 v[82:85], v[182:185], v[218:221], v[82:85]
	v_mfma_f32_16x16x32_bf16 v[82:85], v[186:189], v[222:225], v[82:85]
	v_mfma_f32_16x16x32_bf16 v[70:73], v[154:157], v[226:229], v[70:73]
	v_mfma_f32_16x16x32_bf16 v[70:73], v[158:161], v[230:233], v[70:73]
	v_mfma_f32_16x16x32_bf16 v[66:69], v[182:185], v[226:229], v[66:69]
	v_mfma_f32_16x16x32_bf16 v[66:69], v[186:189], v[230:233], v[66:69]
	s_barrier
	ds_read_b128 v[190:193], v141 offset:16384
	ds_read_b128 v[194:197], v141 offset:17408
	ds_read_b128 v[198:201], v141 offset:18432
	ds_read_b128 v[214:217], v141 offset:19456
	ds_read_b128 v[218:221], v141 offset:20480
	ds_read_b128 v[222:225], v141 offset:21504
	ds_read_b128 v[226:229], v141 offset:22528
	ds_read_b128 v[230:233], v141 offset:23552
	s_add_i32 m0, s88, 0x10000
	v_lshl_add_u64 v[162:163], s[20:21], 0, v[0:1]
	global_load_lds_dwordx4 v[162:163], off
	s_add_i32 m0, s88, 0x12000
	v_lshl_add_u64 v[202:203], v[162:163], 0, s[64:65]
	global_load_lds_dwordx4 v[202:203], off
	s_add_i32 m0, s88, 0x14000
	v_lshl_add_u64 v[202:203], v[162:163], 0, s[72:73]
	global_load_lds_dwordx4 v[202:203], off
	s_add_i32 m0, s88, 0x16000
	v_lshl_add_u64 v[202:203], v[162:163], 0, s[74:75]
	global_load_lds_dwordx4 v[202:203], off
	v_lshl_add_u64 v[202:203], s[68:69], 0, v[130:131]
	s_mov_b32 m0, s89
	v_lshl_add_u64 v[234:235], v[202:203], 0, s[64:65]
	global_load_lds_dwordx4 v[202:203], off
	s_mov_b32 m0, s90
	s_nop 0
	global_load_lds_dwordx4 v[234:235], off
	s_waitcnt vmcnt(8) lgkmcnt(0)
	s_barrier
	v_mfma_f32_16x16x32_bf16 v[62:65], v[134:137], v[190:193], v[62:65]
	v_mfma_f32_16x16x32_bf16 v[62:65], v[142:145], v[194:197], v[62:65]
	v_mfma_f32_16x16x32_bf16 v[58:61], v[146:149], v[190:193], v[58:61]
	v_mfma_f32_16x16x32_bf16 v[58:61], v[150:153], v[194:197], v[58:61]
	v_mfma_f32_16x16x32_bf16 v[46:49], v[134:137], v[198:201], v[46:49]
	v_mfma_f32_16x16x32_bf16 v[46:49], v[142:145], v[214:217], v[46:49]
	v_mfma_f32_16x16x32_bf16 v[42:45], v[146:149], v[198:201], v[42:45]
	v_mfma_f32_16x16x32_bf16 v[42:45], v[150:153], v[214:217], v[42:45]
	v_mfma_f32_16x16x32_bf16 v[30:33], v[134:137], v[218:221], v[30:33]
	v_mfma_f32_16x16x32_bf16 v[30:33], v[142:145], v[222:225], v[30:33]
	v_mfma_f32_16x16x32_bf16 v[26:29], v[146:149], v[218:221], v[26:29]
	v_mfma_f32_16x16x32_bf16 v[26:29], v[150:153], v[222:225], v[26:29]
	v_mfma_f32_16x16x32_bf16 v[14:17], v[134:137], v[226:229], v[14:17]
	v_mfma_f32_16x16x32_bf16 v[14:17], v[142:145], v[230:233], v[14:17]
	v_mfma_f32_16x16x32_bf16 v[10:13], v[146:149], v[226:229], v[10:13]
	v_mfma_f32_16x16x32_bf16 v[10:13], v[150:153], v[230:233], v[10:13]
	v_mfma_f32_16x16x32_bf16 v[54:57], v[154:157], v[190:193], v[54:57]
	v_mfma_f32_16x16x32_bf16 v[54:57], v[158:161], v[194:197], v[54:57]
	v_mfma_f32_16x16x32_bf16 v[50:53], v[182:185], v[190:193], v[50:53]
	v_mfma_f32_16x16x32_bf16 v[50:53], v[186:189], v[194:197], v[50:53]
	v_mfma_f32_16x16x32_bf16 v[38:41], v[154:157], v[198:201], v[38:41]
	v_mfma_f32_16x16x32_bf16 v[38:41], v[158:161], v[214:217], v[38:41]
	v_mfma_f32_16x16x32_bf16 v[34:37], v[182:185], v[198:201], v[34:37]
	v_mfma_f32_16x16x32_bf16 v[34:37], v[186:189], v[214:217], v[34:37]
	v_mfma_f32_16x16x32_bf16 v[22:25], v[154:157], v[218:221], v[22:25]
	v_mfma_f32_16x16x32_bf16 v[22:25], v[158:161], v[222:225], v[22:25]
	v_mfma_f32_16x16x32_bf16 v[18:21], v[182:185], v[218:221], v[18:21]
	v_mfma_f32_16x16x32_bf16 v[18:21], v[186:189], v[222:225], v[18:21]
	v_mfma_f32_16x16x32_bf16 v[6:9], v[154:157], v[226:229], v[6:9]
	v_mfma_f32_16x16x32_bf16 v[6:9], v[158:161], v[230:233], v[6:9]
	v_mfma_f32_16x16x32_bf16 v[2:5], v[182:185], v[226:229], v[2:5]
	v_mfma_f32_16x16x32_bf16 v[2:5], v[186:189], v[230:233], v[2:5]
	s_barrier
	ds_read_b128 v[134:137], v243 offset:32768
	ds_read_b128 v[142:145], v243 offset:33792
	ds_read_b128 v[146:149], v243 offset:34816
	ds_read_b128 v[150:153], v243 offset:35840
	ds_read_b128 v[154:157], v243 offset:49152
	ds_read_b128 v[158:161], v243 offset:50176
	ds_read_b128 v[182:185], v243 offset:51200
	ds_read_b128 v[186:189], v243 offset:52224
	ds_read_b128 v[190:193], v141 offset:32768
	ds_read_b128 v[194:197], v141 offset:33792
	ds_read_b128 v[198:201], v141 offset:34816
	ds_read_b128 v[214:217], v141 offset:35840
	ds_read_b128 v[218:221], v141 offset:36864
	ds_read_b128 v[222:225], v141 offset:37888
	ds_read_b128 v[226:229], v141 offset:38912
	ds_read_b128 v[230:233], v141 offset:39936
	s_mov_b32 m0, s91
	v_lshl_add_u64 v[234:235], v[202:203], 0, s[72:73]
	global_load_lds_dwordx4 v[234:235], off
	v_lshl_add_u64 v[234:235], v[202:203], 0, s[74:75]
	s_mov_b32 m0, s96
	s_nop 0
	global_load_lds_dwordx4 v[234:235], off
	s_waitcnt vmcnt(8) lgkmcnt(0)
	s_barrier
	v_mfma_f32_16x16x32_bf16 v[126:129], v[134:137], v[190:193], v[126:129]
	v_mfma_f32_16x16x32_bf16 v[126:129], v[142:145], v[194:197], v[126:129]
	v_mfma_f32_16x16x32_bf16 v[122:125], v[146:149], v[190:193], v[122:125]
	v_mfma_f32_16x16x32_bf16 v[122:125], v[150:153], v[194:197], v[122:125]
	v_mfma_f32_16x16x32_bf16 v[110:113], v[134:137], v[198:201], v[110:113]
	v_mfma_f32_16x16x32_bf16 v[110:113], v[142:145], v[214:217], v[110:113]
	v_mfma_f32_16x16x32_bf16 v[106:109], v[146:149], v[198:201], v[106:109]
	v_mfma_f32_16x16x32_bf16 v[106:109], v[150:153], v[214:217], v[106:109]
	v_mfma_f32_16x16x32_bf16 v[94:97], v[134:137], v[218:221], v[94:97]
	v_mfma_f32_16x16x32_bf16 v[94:97], v[142:145], v[222:225], v[94:97]
	v_mfma_f32_16x16x32_bf16 v[90:93], v[146:149], v[218:221], v[90:93]
	v_mfma_f32_16x16x32_bf16 v[90:93], v[150:153], v[222:225], v[90:93]
	v_mfma_f32_16x16x32_bf16 v[78:81], v[134:137], v[226:229], v[78:81]
	v_mfma_f32_16x16x32_bf16 v[78:81], v[142:145], v[230:233], v[78:81]
	v_mfma_f32_16x16x32_bf16 v[74:77], v[146:149], v[226:229], v[74:77]
	v_mfma_f32_16x16x32_bf16 v[74:77], v[150:153], v[230:233], v[74:77]
	v_mfma_f32_16x16x32_bf16 v[118:121], v[154:157], v[190:193], v[118:121]
	v_mfma_f32_16x16x32_bf16 v[118:121], v[158:161], v[194:197], v[118:121]
	v_mfma_f32_16x16x32_bf16 v[114:117], v[182:185], v[190:193], v[114:117]
	v_mfma_f32_16x16x32_bf16 v[114:117], v[186:189], v[194:197], v[114:117]
	v_mfma_f32_16x16x32_bf16 v[102:105], v[154:157], v[198:201], v[102:105]
	v_mfma_f32_16x16x32_bf16 v[102:105], v[158:161], v[214:217], v[102:105]
	v_mfma_f32_16x16x32_bf16 v[98:101], v[182:185], v[198:201], v[98:101]
	v_mfma_f32_16x16x32_bf16 v[98:101], v[186:189], v[214:217], v[98:101]
	v_mfma_f32_16x16x32_bf16 v[86:89], v[154:157], v[218:221], v[86:89]
	v_mfma_f32_16x16x32_bf16 v[86:89], v[158:161], v[222:225], v[86:89]
	v_mfma_f32_16x16x32_bf16 v[82:85], v[182:185], v[218:221], v[82:85]
	v_mfma_f32_16x16x32_bf16 v[82:85], v[186:189], v[222:225], v[82:85]
	v_mfma_f32_16x16x32_bf16 v[70:73], v[154:157], v[226:229], v[70:73]
	v_mfma_f32_16x16x32_bf16 v[70:73], v[158:161], v[230:233], v[70:73]
	v_mfma_f32_16x16x32_bf16 v[66:69], v[182:185], v[226:229], v[66:69]
	v_mfma_f32_16x16x32_bf16 v[66:69], v[186:189], v[230:233], v[66:69]
	s_barrier
	ds_read_b128 v[190:193], v141 offset:49152
	ds_read_b128 v[194:197], v141 offset:50176
	ds_read_b128 v[198:201], v141 offset:51200
	ds_read_b128 v[214:217], v141 offset:52224
	ds_read_b128 v[218:221], v141 offset:53248
	ds_read_b128 v[222:225], v141 offset:54272
	ds_read_b128 v[226:229], v141 offset:55296
	ds_read_b128 v[230:233], v141 offset:56320
	s_add_i32 m0, s88, 0x18000
	v_lshl_add_u64 v[234:235], v[162:163], 0, s[34:35]
	global_load_lds_dwordx4 v[234:235], off
	s_add_i32 m0, s88, 0x1a000
	v_lshl_add_u64 v[234:235], v[162:163], 0, s[80:81]
	global_load_lds_dwordx4 v[234:235], off
	v_lshl_add_u64 v[234:235], v[162:163], 0, s[38:39]
	s_add_i32 m0, s88, 0x1c000
	v_lshl_add_u64 v[162:163], v[162:163], 0, s[86:87]
	global_load_lds_dwordx4 v[234:235], off
	s_add_i32 m0, s88, 0x1e000
	s_nop 0
	global_load_lds_dwordx4 v[162:163], off
	v_lshl_add_u64 v[162:163], v[202:203], 0, s[34:35]
	s_mov_b32 m0, s97
	s_nop 0
	global_load_lds_dwordx4 v[162:163], off
	v_lshl_add_u64 v[162:163], v[202:203], 0, s[80:81]
	s_mov_b32 m0, s58
	s_nop 0
	global_load_lds_dwordx4 v[162:163], off
	s_waitcnt vmcnt(8) lgkmcnt(0)
	s_barrier
	v_mfma_f32_16x16x32_bf16 v[62:65], v[134:137], v[190:193], v[62:65]
	v_mfma_f32_16x16x32_bf16 v[62:65], v[142:145], v[194:197], v[62:65]
	v_mfma_f32_16x16x32_bf16 v[58:61], v[146:149], v[190:193], v[58:61]
	v_mfma_f32_16x16x32_bf16 v[58:61], v[150:153], v[194:197], v[58:61]
	v_mfma_f32_16x16x32_bf16 v[46:49], v[134:137], v[198:201], v[46:49]
	v_mfma_f32_16x16x32_bf16 v[46:49], v[142:145], v[214:217], v[46:49]
	v_mfma_f32_16x16x32_bf16 v[42:45], v[146:149], v[198:201], v[42:45]
	v_mfma_f32_16x16x32_bf16 v[42:45], v[150:153], v[214:217], v[42:45]
	v_mfma_f32_16x16x32_bf16 v[30:33], v[134:137], v[218:221], v[30:33]
	v_mfma_f32_16x16x32_bf16 v[30:33], v[142:145], v[222:225], v[30:33]
	v_mfma_f32_16x16x32_bf16 v[26:29], v[146:149], v[218:221], v[26:29]
	v_mfma_f32_16x16x32_bf16 v[26:29], v[150:153], v[222:225], v[26:29]
	v_mfma_f32_16x16x32_bf16 v[14:17], v[134:137], v[226:229], v[14:17]
	v_mfma_f32_16x16x32_bf16 v[14:17], v[142:145], v[230:233], v[14:17]
	v_mfma_f32_16x16x32_bf16 v[10:13], v[146:149], v[226:229], v[10:13]
	v_mfma_f32_16x16x32_bf16 v[10:13], v[150:153], v[230:233], v[10:13]
	s_add_i32 s84, s84, 2
	s_add_u32 s6, s6, 0x100
	s_addc_u32 s7, s7, 0
	s_add_u32 s49, s49, 0x100
	s_addc_u32 s51, s51, 0
	v_mfma_f32_16x16x32_bf16 v[54:57], v[154:157], v[190:193], v[54:57]
	v_mfma_f32_16x16x32_bf16 v[54:57], v[158:161], v[194:197], v[54:57]
	v_mfma_f32_16x16x32_bf16 v[50:53], v[182:185], v[190:193], v[50:53]
	v_mfma_f32_16x16x32_bf16 v[50:53], v[186:189], v[194:197], v[50:53]
	v_mfma_f32_16x16x32_bf16 v[38:41], v[154:157], v[198:201], v[38:41]
	v_mfma_f32_16x16x32_bf16 v[38:41], v[158:161], v[214:217], v[38:41]
	v_mfma_f32_16x16x32_bf16 v[34:37], v[182:185], v[198:201], v[34:37]
	v_mfma_f32_16x16x32_bf16 v[34:37], v[186:189], v[214:217], v[34:37]
	v_mfma_f32_16x16x32_bf16 v[22:25], v[154:157], v[218:221], v[22:25]
	v_mfma_f32_16x16x32_bf16 v[22:25], v[158:161], v[222:225], v[22:25]
	v_mfma_f32_16x16x32_bf16 v[18:21], v[182:185], v[218:221], v[18:21]
	v_mfma_f32_16x16x32_bf16 v[18:21], v[186:189], v[222:225], v[18:21]
	v_mfma_f32_16x16x32_bf16 v[6:9], v[154:157], v[226:229], v[6:9]
	v_mfma_f32_16x16x32_bf16 v[6:9], v[158:161], v[230:233], v[6:9]
	v_mfma_f32_16x16x32_bf16 v[2:5], v[182:185], v[226:229], v[2:5]
	v_mfma_f32_16x16x32_bf16 v[2:5], v[186:189], v[230:233], v[2:5]
	s_barrier
	s_cmp_gt_u32 s84, 5
	s_cbranch_scc0 .LBB0_604
	s_setprio 0
	s_and_b64 vcc, exec, s[52:53]
	s_cbranch_vccz .LBB0_607
	s_barrier

.Lmid1_778:
	s_add_u32 s20, s76, 0xfffc0080
	s_addc_u32 s21, s77, -1
	s_cmp_eq_u32 vcc_hi, 12
	s_cselect_b32 s79, s61, s21
	s_cselect_b32 s78, s85, s20
	s_cselect_b32 s21, s59, vcc_lo
	s_cselect_b32 s20, s86, s87
	s_add_i32 m0, s43, 0xc000
	v_lshl_add_u64 v[202:203], s[76:77], 0, v[182:183]
	global_load_lds_dwordx4 v[202:203], off
	s_add_i32 m0, s43, 0xe000
	v_lshl_add_u64 v[202:203], v[202:203], 0, s[72:73]
	global_load_lds_dwordx4 v[202:203], off
	s_waitcnt vmcnt(8) lgkmcnt(0)
	s_barrier
	v_mfma_f32_16x16x32_bf16 v[126:129], v[130:133], v[184:187], 0
	v_mfma_f32_16x16x32_bf16 v[126:129], v[134:137], v[188:191], v[126:129]
	v_mfma_f32_16x16x32_bf16 v[122:125], v[138:141], v[184:187], 0
	v_mfma_f32_16x16x32_bf16 v[122:125], v[142:145], v[188:191], v[122:125]
	v_mfma_f32_16x16x32_bf16 v[110:113], v[130:133], v[198:201], 0
	v_mfma_f32_16x16x32_bf16 v[110:113], v[134:137], v[214:217], v[110:113]
	v_mfma_f32_16x16x32_bf16 v[106:109], v[138:141], v[198:201], 0
	v_mfma_f32_16x16x32_bf16 v[106:109], v[142:145], v[214:217], v[106:109]
	v_mfma_f32_16x16x32_bf16 v[94:97], v[130:133], v[218:221], 0
	v_mfma_f32_16x16x32_bf16 v[94:97], v[134:137], v[222:225], v[94:97]
	v_mfma_f32_16x16x32_bf16 v[90:93], v[138:141], v[218:221], 0
	v_mfma_f32_16x16x32_bf16 v[90:93], v[142:145], v[222:225], v[90:93]
	v_mfma_f32_16x16x32_bf16 v[78:81], v[130:133], v[226:229], 0
	v_mfma_f32_16x16x32_bf16 v[78:81], v[134:137], v[230:233], v[78:81]
	v_mfma_f32_16x16x32_bf16 v[74:77], v[138:141], v[226:229], 0
	v_mfma_f32_16x16x32_bf16 v[74:77], v[142:145], v[230:233], v[74:77]
	v_mfma_f32_16x16x32_bf16 v[118:121], v[146:149], v[184:187], 0
	v_mfma_f32_16x16x32_bf16 v[118:121], v[150:153], v[188:191], v[118:121]
	v_mfma_f32_16x16x32_bf16 v[114:117], v[154:157], v[184:187], 0
	v_mfma_f32_16x16x32_bf16 v[114:117], v[158:161], v[188:191], v[114:117]
	v_mfma_f32_16x16x32_bf16 v[102:105], v[146:149], v[198:201], 0
	v_mfma_f32_16x16x32_bf16 v[102:105], v[150:153], v[214:217], v[102:105]
	v_mfma_f32_16x16x32_bf16 v[98:101], v[154:157], v[198:201], 0
	v_mfma_f32_16x16x32_bf16 v[98:101], v[158:161], v[214:217], v[98:101]
	v_mfma_f32_16x16x32_bf16 v[86:89], v[146:149], v[218:221], 0
	v_mfma_f32_16x16x32_bf16 v[86:89], v[150:153], v[222:225], v[86:89]
	v_mfma_f32_16x16x32_bf16 v[82:85], v[154:157], v[218:221], 0
	v_mfma_f32_16x16x32_bf16 v[82:85], v[158:161], v[222:225], v[82:85]
	v_mfma_f32_16x16x32_bf16 v[70:73], v[146:149], v[226:229], 0
	v_mfma_f32_16x16x32_bf16 v[70:73], v[150:153], v[230:233], v[70:73]
	v_mfma_f32_16x16x32_bf16 v[66:69], v[154:157], v[226:229], 0
	v_mfma_f32_16x16x32_bf16 v[66:69], v[158:161], v[230:233], v[66:69]
	s_barrier
	ds_read_b128 v[184:187], v196 offset:16384
	ds_read_b128 v[188:191], v196 offset:17408
	ds_read_b128 v[198:201], v196 offset:18432
	ds_read_b128 v[214:217], v196 offset:19456
	ds_read_b128 v[218:221], v196 offset:20480
	ds_read_b128 v[222:225], v196 offset:21504
	ds_read_b128 v[226:229], v196 offset:22528
	ds_read_b128 v[230:233], v196 offset:23552
	s_add_i32 m0, s14, 0x10000
	v_lshl_add_u64 v[202:203], s[20:21], 0, v[0:1]
	global_load_lds_dwordx4 v[202:203], off
	s_add_i32 m0, s14, 0x12000
	v_lshl_add_u64 v[234:235], v[202:203], 0, s[72:73]
	global_load_lds_dwordx4 v[234:235], off
	s_add_i32 m0, s14, 0x14000
	v_lshl_add_u64 v[234:235], v[202:203], 0, s[28:29]
	global_load_lds_dwordx4 v[234:235], off
	s_add_i32 m0, s14, 0x16000
	v_lshl_add_u64 v[234:235], v[202:203], 0, s[82:83]
	global_load_lds_dwordx4 v[234:235], off
	v_lshl_add_u64 v[234:235], s[78:79], 0, v[162:163]
	s_mov_b32 m0, s43
	v_lshl_add_u64 v[236:237], v[234:235], 0, s[72:73]
	global_load_lds_dwordx4 v[234:235], off
	s_mov_b32 m0, s46
	s_nop 0
	global_load_lds_dwordx4 v[236:237], off
	s_waitcnt vmcnt(8) lgkmcnt(0)
	s_barrier
	v_mfma_f32_16x16x32_bf16 v[62:65], v[130:133], v[184:187], 0
	v_mfma_f32_16x16x32_bf16 v[62:65], v[134:137], v[188:191], v[62:65]
	v_mfma_f32_16x16x32_bf16 v[58:61], v[138:141], v[184:187], 0
	v_mfma_f32_16x16x32_bf16 v[58:61], v[142:145], v[188:191], v[58:61]
	v_mfma_f32_16x16x32_bf16 v[46:49], v[130:133], v[198:201], 0
	v_mfma_f32_16x16x32_bf16 v[46:49], v[134:137], v[214:217], v[46:49]
	v_mfma_f32_16x16x32_bf16 v[42:45], v[138:141], v[198:201], 0
	v_mfma_f32_16x16x32_bf16 v[42:45], v[142:145], v[214:217], v[42:45]
	v_mfma_f32_16x16x32_bf16 v[30:33], v[130:133], v[218:221], 0
	v_mfma_f32_16x16x32_bf16 v[30:33], v[134:137], v[222:225], v[30:33]
	v_mfma_f32_16x16x32_bf16 v[26:29], v[138:141], v[218:221], 0
	v_mfma_f32_16x16x32_bf16 v[26:29], v[142:145], v[222:225], v[26:29]
	v_mfma_f32_16x16x32_bf16 v[14:17], v[130:133], v[226:229], 0
	v_mfma_f32_16x16x32_bf16 v[14:17], v[134:137], v[230:233], v[14:17]
	v_mfma_f32_16x16x32_bf16 v[10:13], v[138:141], v[226:229], 0
	v_mfma_f32_16x16x32_bf16 v[10:13], v[142:145], v[230:233], v[10:13]
	v_mfma_f32_16x16x32_bf16 v[54:57], v[146:149], v[184:187], 0
	v_mfma_f32_16x16x32_bf16 v[54:57], v[150:153], v[188:191], v[54:57]
	v_mfma_f32_16x16x32_bf16 v[50:53], v[154:157], v[184:187], 0
	v_mfma_f32_16x16x32_bf16 v[50:53], v[158:161], v[188:191], v[50:53]
	v_mfma_f32_16x16x32_bf16 v[38:41], v[146:149], v[198:201], 0
	v_mfma_f32_16x16x32_bf16 v[38:41], v[150:153], v[214:217], v[38:41]
	v_mfma_f32_16x16x32_bf16 v[34:37], v[154:157], v[198:201], 0
	v_mfma_f32_16x16x32_bf16 v[34:37], v[158:161], v[214:217], v[34:37]
	v_mfma_f32_16x16x32_bf16 v[22:25], v[146:149], v[218:221], 0
	v_mfma_f32_16x16x32_bf16 v[22:25], v[150:153], v[222:225], v[22:25]
	v_mfma_f32_16x16x32_bf16 v[18:21], v[154:157], v[218:221], 0
	v_mfma_f32_16x16x32_bf16 v[18:21], v[158:161], v[222:225], v[18:21]
	v_mfma_f32_16x16x32_bf16 v[6:9], v[146:149], v[226:229], 0
	v_mfma_f32_16x16x32_bf16 v[6:9], v[150:153], v[230:233], v[6:9]
	v_mfma_f32_16x16x32_bf16 v[2:5], v[154:157], v[226:229], 0
	v_mfma_f32_16x16x32_bf16 v[2:5], v[158:161], v[230:233], v[2:5]
	s_barrier
	ds_read_b128 v[130:133], v243 offset:32768
	ds_read_b128 v[134:137], v243 offset:33792
	ds_read_b128 v[138:141], v243 offset:34816
	ds_read_b128 v[142:145], v243 offset:35840
	ds_read_b128 v[146:149], v243 offset:49152
	ds_read_b128 v[150:153], v243 offset:50176
	ds_read_b128 v[154:157], v243 offset:51200
	ds_read_b128 v[158:161], v243 offset:52224
	ds_read_b128 v[184:187], v196 offset:32768
	ds_read_b128 v[188:191], v196 offset:33792
	ds_read_b128 v[198:201], v196 offset:34816
	ds_read_b128 v[214:217], v196 offset:35840
	ds_read_b128 v[218:221], v196 offset:36864
	ds_read_b128 v[222:225], v196 offset:37888
	ds_read_b128 v[226:229], v196 offset:38912
	ds_read_b128 v[230:233], v196 offset:39936
	s_mov_b32 m0, s47
	v_lshl_add_u64 v[236:237], v[234:235], 0, s[28:29]
	global_load_lds_dwordx4 v[236:237], off
	v_lshl_add_u64 v[236:237], v[234:235], 0, s[82:83]
	s_mov_b32 m0, s88
	s_nop 0
	global_load_lds_dwordx4 v[236:237], off
	s_waitcnt vmcnt(8) lgkmcnt(0)
	s_barrier
	v_mfma_f32_16x16x32_bf16 v[126:129], v[130:133], v[184:187], v[126:129]
	v_mfma_f32_16x16x32_bf16 v[126:129], v[134:137], v[188:191], v[126:129]
	v_mfma_f32_16x16x32_bf16 v[122:125], v[138:141], v[184:187], v[122:125]
	v_mfma_f32_16x16x32_bf16 v[122:125], v[142:145], v[188:191], v[122:125]
	v_mfma_f32_16x16x32_bf16 v[110:113], v[130:133], v[198:201], v[110:113]
	v_mfma_f32_16x16x32_bf16 v[110:113], v[134:137], v[214:217], v[110:113]
	v_mfma_f32_16x16x32_bf16 v[106:109], v[138:141], v[198:201], v[106:109]
	v_mfma_f32_16x16x32_bf16 v[106:109], v[142:145], v[214:217], v[106:109]
	v_mfma_f32_16x16x32_bf16 v[94:97], v[130:133], v[218:221], v[94:97]
	v_mfma_f32_16x16x32_bf16 v[94:97], v[134:137], v[222:225], v[94:97]
	v_mfma_f32_16x16x32_bf16 v[90:93], v[138:141], v[218:221], v[90:93]
	v_mfma_f32_16x16x32_bf16 v[90:93], v[142:145], v[222:225], v[90:93]
	v_mfma_f32_16x16x32_bf16 v[78:81], v[130:133], v[226:229], v[78:81]
	v_mfma_f32_16x16x32_bf16 v[78:81], v[134:137], v[230:233], v[78:81]
	v_mfma_f32_16x16x32_bf16 v[74:77], v[138:141], v[226:229], v[74:77]
	v_mfma_f32_16x16x32_bf16 v[74:77], v[142:145], v[230:233], v[74:77]
	v_mfma_f32_16x16x32_bf16 v[118:121], v[146:149], v[184:187], v[118:121]
	v_mfma_f32_16x16x32_bf16 v[118:121], v[150:153], v[188:191], v[118:121]
	v_mfma_f32_16x16x32_bf16 v[114:117], v[154:157], v[184:187], v[114:117]
	v_mfma_f32_16x16x32_bf16 v[114:117], v[158:161], v[188:191], v[114:117]
	v_mfma_f32_16x16x32_bf16 v[102:105], v[146:149], v[198:201], v[102:105]
	v_mfma_f32_16x16x32_bf16 v[102:105], v[150:153], v[214:217], v[102:105]
	v_mfma_f32_16x16x32_bf16 v[98:101], v[154:157], v[198:201], v[98:101]
	v_mfma_f32_16x16x32_bf16 v[98:101], v[158:161], v[214:217], v[98:101]
	v_mfma_f32_16x16x32_bf16 v[86:89], v[146:149], v[218:221], v[86:89]
	v_mfma_f32_16x16x32_bf16 v[86:89], v[150:153], v[222:225], v[86:89]
	v_mfma_f32_16x16x32_bf16 v[82:85], v[154:157], v[218:221], v[82:85]
	v_mfma_f32_16x16x32_bf16 v[82:85], v[158:161], v[222:225], v[82:85]
	v_mfma_f32_16x16x32_bf16 v[70:73], v[146:149], v[226:229], v[70:73]
	v_mfma_f32_16x16x32_bf16 v[70:73], v[150:153], v[230:233], v[70:73]
	v_mfma_f32_16x16x32_bf16 v[66:69], v[154:157], v[226:229], v[66:69]
	v_mfma_f32_16x16x32_bf16 v[66:69], v[158:161], v[230:233], v[66:69]
	s_barrier
	ds_read_b128 v[184:187], v196 offset:49152
	ds_read_b128 v[188:191], v196 offset:50176
	ds_read_b128 v[198:201], v196 offset:51200
	ds_read_b128 v[214:217], v196 offset:52224
	ds_read_b128 v[218:221], v196 offset:53248
	ds_read_b128 v[222:225], v196 offset:54272
	ds_read_b128 v[226:229], v196 offset:55296
	ds_read_b128 v[230:233], v196 offset:56320
	s_add_i32 m0, s14, 0x18000
	v_lshl_add_u64 v[236:237], v[202:203], 0, s[34:35]
	global_load_lds_dwordx4 v[236:237], off
	s_add_i32 m0, s14, 0x1a000
	v_lshl_add_u64 v[236:237], v[202:203], 0, s[38:39]
	global_load_lds_dwordx4 v[236:237], off
	v_lshl_add_u64 v[236:237], v[202:203], 0, s[44:45]
	s_add_i32 m0, s14, 0x1c000
	v_lshl_add_u64 v[202:203], v[202:203], 0, s[10:11]
	global_load_lds_dwordx4 v[236:237], off
	s_add_i32 m0, s14, 0x1e000
	s_nop 0
	global_load_lds_dwordx4 v[202:203], off
	v_lshl_add_u64 v[202:203], v[234:235], 0, s[34:35]
	s_mov_b32 m0, s89
	s_nop 0
	global_load_lds_dwordx4 v[202:203], off
	v_lshl_add_u64 v[202:203], v[234:235], 0, s[38:39]
	s_mov_b32 m0, s90
	s_nop 0
	global_load_lds_dwordx4 v[202:203], off
	s_waitcnt vmcnt(8) lgkmcnt(0)
	s_barrier
	v_mfma_f32_16x16x32_bf16 v[62:65], v[130:133], v[184:187], v[62:65]
	v_mfma_f32_16x16x32_bf16 v[62:65], v[134:137], v[188:191], v[62:65]
	v_mfma_f32_16x16x32_bf16 v[58:61], v[138:141], v[184:187], v[58:61]
	v_mfma_f32_16x16x32_bf16 v[58:61], v[142:145], v[188:191], v[58:61]
	v_mfma_f32_16x16x32_bf16 v[46:49], v[130:133], v[198:201], v[46:49]
	v_mfma_f32_16x16x32_bf16 v[46:49], v[134:137], v[214:217], v[46:49]
	v_mfma_f32_16x16x32_bf16 v[42:45], v[138:141], v[198:201], v[42:45]
	v_mfma_f32_16x16x32_bf16 v[42:45], v[142:145], v[214:217], v[42:45]
	v_mfma_f32_16x16x32_bf16 v[30:33], v[130:133], v[218:221], v[30:33]
	v_mfma_f32_16x16x32_bf16 v[30:33], v[134:137], v[222:225], v[30:33]
	v_mfma_f32_16x16x32_bf16 v[26:29], v[138:141], v[218:221], v[26:29]
	v_mfma_f32_16x16x32_bf16 v[26:29], v[142:145], v[222:225], v[26:29]
	v_mfma_f32_16x16x32_bf16 v[14:17], v[130:133], v[226:229], v[14:17]
	v_mfma_f32_16x16x32_bf16 v[14:17], v[134:137], v[230:233], v[14:17]
	v_mfma_f32_16x16x32_bf16 v[10:13], v[138:141], v[226:229], v[10:13]
	v_mfma_f32_16x16x32_bf16 v[10:13], v[142:145], v[230:233], v[10:13]
	s_add_i32 vcc_hi, vcc_hi, 2
	s_add_u32 s76, s76, 0x100
	s_addc_u32 s77, s77, 0
	s_add_u32 s87, s87, 0x100
	s_addc_u32 vcc_lo, vcc_lo, 0
	v_mfma_f32_16x16x32_bf16 v[54:57], v[146:149], v[184:187], v[54:57]
	v_mfma_f32_16x16x32_bf16 v[54:57], v[150:153], v[188:191], v[54:57]
	v_mfma_f32_16x16x32_bf16 v[50:53], v[154:157], v[184:187], v[50:53]
	v_mfma_f32_16x16x32_bf16 v[50:53], v[158:161], v[188:191], v[50:53]
	v_mfma_f32_16x16x32_bf16 v[38:41], v[146:149], v[198:201], v[38:41]
	v_mfma_f32_16x16x32_bf16 v[38:41], v[150:153], v[214:217], v[38:41]
	v_mfma_f32_16x16x32_bf16 v[34:37], v[154:157], v[198:201], v[34:37]
	v_mfma_f32_16x16x32_bf16 v[34:37], v[158:161], v[214:217], v[34:37]
	v_mfma_f32_16x16x32_bf16 v[22:25], v[146:149], v[218:221], v[22:25]
	v_mfma_f32_16x16x32_bf16 v[22:25], v[150:153], v[222:225], v[22:25]
	v_mfma_f32_16x16x32_bf16 v[18:21], v[154:157], v[218:221], v[18:21]
	v_mfma_f32_16x16x32_bf16 v[18:21], v[158:161], v[222:225], v[18:21]
	v_mfma_f32_16x16x32_bf16 v[6:9], v[146:149], v[226:229], v[6:9]
	v_mfma_f32_16x16x32_bf16 v[6:9], v[150:153], v[230:233], v[6:9]
	v_mfma_f32_16x16x32_bf16 v[2:5], v[154:157], v[226:229], v[2:5]
	v_mfma_f32_16x16x32_bf16 v[2:5], v[158:161], v[230:233], v[2:5]
	s_barrier
	s_branch .LBB0_778
	.p2alignl 6, 3212836864
.LBB0_778:
	ds_read_b128 v[130:133], v243
	ds_read_b128 v[134:137], v243 offset:1024
	ds_read_b128 v[138:141], v243 offset:2048
	ds_read_b128 v[142:145], v243 offset:3072
	ds_read_b128 v[146:149], v243 offset:16384
	ds_read_b128 v[150:153], v243 offset:17408
	ds_read_b128 v[154:157], v243 offset:18432
	ds_read_b128 v[158:161], v243 offset:19456
	ds_read_b128 v[184:187], v196
	ds_read_b128 v[188:191], v196 offset:1024
	ds_read_b128 v[198:201], v196 offset:2048
	ds_read_b128 v[214:217], v196 offset:3072
	ds_read_b128 v[218:221], v196 offset:4096
	ds_read_b128 v[222:225], v196 offset:5120
	ds_read_b128 v[226:229], v196 offset:6144
	ds_read_b128 v[230:233], v196 offset:7168
	s_add_u32 s20, s76, 0xfffc0080
	s_addc_u32 s21, s77, -1
	s_cmp_eq_u32 vcc_hi, 12
	s_cselect_b32 s79, s61, s21
	s_cselect_b32 s78, s85, s20
	s_cselect_b32 s21, s59, vcc_lo
	s_cselect_b32 s20, s86, s87
	s_add_i32 m0, s43, 0xc000
	v_lshl_add_u64 v[202:203], s[76:77], 0, v[182:183]
	global_load_lds_dwordx4 v[202:203], off
	s_add_i32 m0, s43, 0xe000
	v_lshl_add_u64 v[202:203], v[202:203], 0, s[72:73]
	global_load_lds_dwordx4 v[202:203], off
	s_waitcnt vmcnt(8) lgkmcnt(0)
	s_barrier
	v_mfma_f32_16x16x32_bf16 v[126:129], v[130:133], v[184:187], v[126:129]
	v_mfma_f32_16x16x32_bf16 v[126:129], v[134:137], v[188:191], v[126:129]
	v_mfma_f32_16x16x32_bf16 v[122:125], v[138:141], v[184:187], v[122:125]
	v_mfma_f32_16x16x32_bf16 v[122:125], v[142:145], v[188:191], v[122:125]
	v_mfma_f32_16x16x32_bf16 v[110:113], v[130:133], v[198:201], v[110:113]
	v_mfma_f32_16x16x32_bf16 v[110:113], v[134:137], v[214:217], v[110:113]
	v_mfma_f32_16x16x32_bf16 v[106:109], v[138:141], v[198:201], v[106:109]
	v_mfma_f32_16x16x32_bf16 v[106:109], v[142:145], v[214:217], v[106:109]
	v_mfma_f32_16x16x32_bf16 v[94:97], v[130:133], v[218:221], v[94:97]
	v_mfma_f32_16x16x32_bf16 v[94:97], v[134:137], v[222:225], v[94:97]
	v_mfma_f32_16x16x32_bf16 v[90:93], v[138:141], v[218:221], v[90:93]
	v_mfma_f32_16x16x32_bf16 v[90:93], v[142:145], v[222:225], v[90:93]
	v_mfma_f32_16x16x32_bf16 v[78:81], v[130:133], v[226:229], v[78:81]
	v_mfma_f32_16x16x32_bf16 v[78:81], v[134:137], v[230:233], v[78:81]
	v_mfma_f32_16x16x32_bf16 v[74:77], v[138:141], v[226:229], v[74:77]
	v_mfma_f32_16x16x32_bf16 v[74:77], v[142:145], v[230:233], v[74:77]
	v_mfma_f32_16x16x32_bf16 v[118:121], v[146:149], v[184:187], v[118:121]
	v_mfma_f32_16x16x32_bf16 v[118:121], v[150:153], v[188:191], v[118:121]
	v_mfma_f32_16x16x32_bf16 v[114:117], v[154:157], v[184:187], v[114:117]
	v_mfma_f32_16x16x32_bf16 v[114:117], v[158:161], v[188:191], v[114:117]
	v_mfma_f32_16x16x32_bf16 v[102:105], v[146:149], v[198:201], v[102:105]
	v_mfma_f32_16x16x32_bf16 v[102:105], v[150:153], v[214:217], v[102:105]
	v_mfma_f32_16x16x32_bf16 v[98:101], v[154:157], v[198:201], v[98:101]
	v_mfma_f32_16x16x32_bf16 v[98:101], v[158:161], v[214:217], v[98:101]
	v_mfma_f32_16x16x32_bf16 v[86:89], v[146:149], v[218:221], v[86:89]
	v_mfma_f32_16x16x32_bf16 v[86:89], v[150:153], v[222:225], v[86:89]
	v_mfma_f32_16x16x32_bf16 v[82:85], v[154:157], v[218:221], v[82:85]
	v_mfma_f32_16x16x32_bf16 v[82:85], v[158:161], v[222:225], v[82:85]
	v_mfma_f32_16x16x32_bf16 v[70:73], v[146:149], v[226:229], v[70:73]
	v_mfma_f32_16x16x32_bf16 v[70:73], v[150:153], v[230:233], v[70:73]
	v_mfma_f32_16x16x32_bf16 v[66:69], v[154:157], v[226:229], v[66:69]
	v_mfma_f32_16x16x32_bf16 v[66:69], v[158:161], v[230:233], v[66:69]
	s_barrier
	ds_read_b128 v[184:187], v196 offset:16384
	ds_read_b128 v[188:191], v196 offset:17408
	ds_read_b128 v[198:201], v196 offset:18432
	ds_read_b128 v[214:217], v196 offset:19456
	ds_read_b128 v[218:221], v196 offset:20480
	ds_read_b128 v[222:225], v196 offset:21504
	ds_read_b128 v[226:229], v196 offset:22528
	ds_read_b128 v[230:233], v196 offset:23552
	s_add_i32 m0, s14, 0x10000
	v_lshl_add_u64 v[202:203], s[20:21], 0, v[0:1]
	global_load_lds_dwordx4 v[202:203], off
	s_add_i32 m0, s14, 0x12000
	v_lshl_add_u64 v[234:235], v[202:203], 0, s[72:73]
	global_load_lds_dwordx4 v[234:235], off
	s_add_i32 m0, s14, 0x14000
	v_lshl_add_u64 v[234:235], v[202:203], 0, s[28:29]
	global_load_lds_dwordx4 v[234:235], off
	s_add_i32 m0, s14, 0x16000
	v_lshl_add_u64 v[234:235], v[202:203], 0, s[82:83]
	global_load_lds_dwordx4 v[234:235], off
	v_lshl_add_u64 v[234:235], s[78:79], 0, v[162:163]
	s_mov_b32 m0, s43
	v_lshl_add_u64 v[236:237], v[234:235], 0, s[72:73]
	global_load_lds_dwordx4 v[234:235], off
	s_mov_b32 m0, s46
	s_nop 0
	global_load_lds_dwordx4 v[236:237], off
	s_waitcnt vmcnt(8) lgkmcnt(0)
	s_barrier
	v_mfma_f32_16x16x32_bf16 v[62:65], v[130:133], v[184:187], v[62:65]
	v_mfma_f32_16x16x32_bf16 v[62:65], v[134:137], v[188:191], v[62:65]
	v_mfma_f32_16x16x32_bf16 v[58:61], v[138:141], v[184:187], v[58:61]
	v_mfma_f32_16x16x32_bf16 v[58:61], v[142:145], v[188:191], v[58:61]
	v_mfma_f32_16x16x32_bf16 v[46:49], v[130:133], v[198:201], v[46:49]
	v_mfma_f32_16x16x32_bf16 v[46:49], v[134:137], v[214:217], v[46:49]
	v_mfma_f32_16x16x32_bf16 v[42:45], v[138:141], v[198:201], v[42:45]
	v_mfma_f32_16x16x32_bf16 v[42:45], v[142:145], v[214:217], v[42:45]
	v_mfma_f32_16x16x32_bf16 v[30:33], v[130:133], v[218:221], v[30:33]
	v_mfma_f32_16x16x32_bf16 v[30:33], v[134:137], v[222:225], v[30:33]
	v_mfma_f32_16x16x32_bf16 v[26:29], v[138:141], v[218:221], v[26:29]
	v_mfma_f32_16x16x32_bf16 v[26:29], v[142:145], v[222:225], v[26:29]
	v_mfma_f32_16x16x32_bf16 v[14:17], v[130:133], v[226:229], v[14:17]
	v_mfma_f32_16x16x32_bf16 v[14:17], v[134:137], v[230:233], v[14:17]
	v_mfma_f32_16x16x32_bf16 v[10:13], v[138:141], v[226:229], v[10:13]
	v_mfma_f32_16x16x32_bf16 v[10:13], v[142:145], v[230:233], v[10:13]
	v_mfma_f32_16x16x32_bf16 v[54:57], v[146:149], v[184:187], v[54:57]
	v_mfma_f32_16x16x32_bf16 v[54:57], v[150:153], v[188:191], v[54:57]
	v_mfma_f32_16x16x32_bf16 v[50:53], v[154:157], v[184:187], v[50:53]
	v_mfma_f32_16x16x32_bf16 v[50:53], v[158:161], v[188:191], v[50:53]
	v_mfma_f32_16x16x32_bf16 v[38:41], v[146:149], v[198:201], v[38:41]
	v_mfma_f32_16x16x32_bf16 v[38:41], v[150:153], v[214:217], v[38:41]
	v_mfma_f32_16x16x32_bf16 v[34:37], v[154:157], v[198:201], v[34:37]
	v_mfma_f32_16x16x32_bf16 v[34:37], v[158:161], v[214:217], v[34:37]
	v_mfma_f32_16x16x32_bf16 v[22:25], v[146:149], v[218:221], v[22:25]
	v_mfma_f32_16x16x32_bf16 v[22:25], v[150:153], v[222:225], v[22:25]
	v_mfma_f32_16x16x32_bf16 v[18:21], v[154:157], v[218:221], v[18:21]
	v_mfma_f32_16x16x32_bf16 v[18:21], v[158:161], v[222:225], v[18:21]
	v_mfma_f32_16x16x32_bf16 v[6:9], v[146:149], v[226:229], v[6:9]
	v_mfma_f32_16x16x32_bf16 v[6:9], v[150:153], v[230:233], v[6:9]
	v_mfma_f32_16x16x32_bf16 v[2:5], v[154:157], v[226:229], v[2:5]
	v_mfma_f32_16x16x32_bf16 v[2:5], v[158:161], v[230:233], v[2:5]
	s_barrier
	ds_read_b128 v[130:133], v243 offset:32768
	ds_read_b128 v[134:137], v243 offset:33792
	ds_read_b128 v[138:141], v243 offset:34816
	ds_read_b128 v[142:145], v243 offset:35840
	ds_read_b128 v[146:149], v243 offset:49152
	ds_read_b128 v[150:153], v243 offset:50176
	ds_read_b128 v[154:157], v243 offset:51200
	ds_read_b128 v[158:161], v243 offset:52224
	ds_read_b128 v[184:187], v196 offset:32768
	ds_read_b128 v[188:191], v196 offset:33792
	ds_read_b128 v[198:201], v196 offset:34816
	ds_read_b128 v[214:217], v196 offset:35840
	ds_read_b128 v[218:221], v196 offset:36864
	ds_read_b128 v[222:225], v196 offset:37888
	ds_read_b128 v[226:229], v196 offset:38912
	ds_read_b128 v[230:233], v196 offset:39936
	s_mov_b32 m0, s47
	v_lshl_add_u64 v[236:237], v[234:235], 0, s[28:29]
	global_load_lds_dwordx4 v[236:237], off
	v_lshl_add_u64 v[236:237], v[234:235], 0, s[82:83]
	s_mov_b32 m0, s88
	s_nop 0
	global_load_lds_dwordx4 v[236:237], off
	s_waitcnt vmcnt(8) lgkmcnt(0)
	s_barrier
	v_mfma_f32_16x16x32_bf16 v[126:129], v[130:133], v[184:187], v[126:129]
	v_mfma_f32_16x16x32_bf16 v[126:129], v[134:137], v[188:191], v[126:129]
	v_mfma_f32_16x16x32_bf16 v[122:125], v[138:141], v[184:187], v[122:125]
	v_mfma_f32_16x16x32_bf16 v[122:125], v[142:145], v[188:191], v[122:125]
	v_mfma_f32_16x16x32_bf16 v[110:113], v[130:133], v[198:201], v[110:113]
	v_mfma_f32_16x16x32_bf16 v[110:113], v[134:137], v[214:217], v[110:113]
	v_mfma_f32_16x16x32_bf16 v[106:109], v[138:141], v[198:201], v[106:109]
	v_mfma_f32_16x16x32_bf16 v[106:109], v[142:145], v[214:217], v[106:109]
	v_mfma_f32_16x16x32_bf16 v[94:97], v[130:133], v[218:221], v[94:97]
	v_mfma_f32_16x16x32_bf16 v[94:97], v[134:137], v[222:225], v[94:97]
	v_mfma_f32_16x16x32_bf16 v[90:93], v[138:141], v[218:221], v[90:93]
	v_mfma_f32_16x16x32_bf16 v[90:93], v[142:145], v[222:225], v[90:93]
	v_mfma_f32_16x16x32_bf16 v[78:81], v[130:133], v[226:229], v[78:81]
	v_mfma_f32_16x16x32_bf16 v[78:81], v[134:137], v[230:233], v[78:81]
	v_mfma_f32_16x16x32_bf16 v[74:77], v[138:141], v[226:229], v[74:77]
	v_mfma_f32_16x16x32_bf16 v[74:77], v[142:145], v[230:233], v[74:77]
	v_mfma_f32_16x16x32_bf16 v[118:121], v[146:149], v[184:187], v[118:121]
	v_mfma_f32_16x16x32_bf16 v[118:121], v[150:153], v[188:191], v[118:121]
	v_mfma_f32_16x16x32_bf16 v[114:117], v[154:157], v[184:187], v[114:117]
	v_mfma_f32_16x16x32_bf16 v[114:117], v[158:161], v[188:191], v[114:117]
	v_mfma_f32_16x16x32_bf16 v[102:105], v[146:149], v[198:201], v[102:105]
	v_mfma_f32_16x16x32_bf16 v[102:105], v[150:153], v[214:217], v[102:105]
	v_mfma_f32_16x16x32_bf16 v[98:101], v[154:157], v[198:201], v[98:101]
	v_mfma_f32_16x16x32_bf16 v[98:101], v[158:161], v[214:217], v[98:101]
	v_mfma_f32_16x16x32_bf16 v[86:89], v[146:149], v[218:221], v[86:89]
	v_mfma_f32_16x16x32_bf16 v[86:89], v[150:153], v[222:225], v[86:89]
	v_mfma_f32_16x16x32_bf16 v[82:85], v[154:157], v[218:221], v[82:85]
	v_mfma_f32_16x16x32_bf16 v[82:85], v[158:161], v[222:225], v[82:85]
	v_mfma_f32_16x16x32_bf16 v[70:73], v[146:149], v[226:229], v[70:73]
	v_mfma_f32_16x16x32_bf16 v[70:73], v[150:153], v[230:233], v[70:73]
	v_mfma_f32_16x16x32_bf16 v[66:69], v[154:157], v[226:229], v[66:69]
	v_mfma_f32_16x16x32_bf16 v[66:69], v[158:161], v[230:233], v[66:69]
	s_barrier
	ds_read_b128 v[184:187], v196 offset:49152
	ds_read_b128 v[188:191], v196 offset:50176
	ds_read_b128 v[198:201], v196 offset:51200
	ds_read_b128 v[214:217], v196 offset:52224
	ds_read_b128 v[218:221], v196 offset:53248
	ds_read_b128 v[222:225], v196 offset:54272
	ds_read_b128 v[226:229], v196 offset:55296
	ds_read_b128 v[230:233], v196 offset:56320
	s_add_i32 m0, s14, 0x18000
	v_lshl_add_u64 v[236:237], v[202:203], 0, s[34:35]
	global_load_lds_dwordx4 v[236:237], off
	s_add_i32 m0, s14, 0x1a000
	v_lshl_add_u64 v[236:237], v[202:203], 0, s[38:39]
	global_load_lds_dwordx4 v[236:237], off
	v_lshl_add_u64 v[236:237], v[202:203], 0, s[44:45]
	s_add_i32 m0, s14, 0x1c000
	v_lshl_add_u64 v[202:203], v[202:203], 0, s[10:11]
	global_load_lds_dwordx4 v[236:237], off
	s_add_i32 m0, s14, 0x1e000
	s_nop 0
	global_load_lds_dwordx4 v[202:203], off
	v_lshl_add_u64 v[202:203], v[234:235], 0, s[34:35]
	s_mov_b32 m0, s89
	s_nop 0
	global_load_lds_dwordx4 v[202:203], off
	v_lshl_add_u64 v[202:203], v[234:235], 0, s[38:39]
	s_mov_b32 m0, s90
	s_nop 0
	global_load_lds_dwordx4 v[202:203], off
	s_waitcnt vmcnt(8) lgkmcnt(0)
	s_barrier
	v_mfma_f32_16x16x32_bf16 v[62:65], v[130:133], v[184:187], v[62:65]
	v_mfma_f32_16x16x32_bf16 v[62:65], v[134:137], v[188:191], v[62:65]
	v_mfma_f32_16x16x32_bf16 v[58:61], v[138:141], v[184:187], v[58:61]
	v_mfma_f32_16x16x32_bf16 v[58:61], v[142:145], v[188:191], v[58:61]
	v_mfma_f32_16x16x32_bf16 v[46:49], v[130:133], v[198:201], v[46:49]
	v_mfma_f32_16x16x32_bf16 v[46:49], v[134:137], v[214:217], v[46:49]
	v_mfma_f32_16x16x32_bf16 v[42:45], v[138:141], v[198:201], v[42:45]
	v_mfma_f32_16x16x32_bf16 v[42:45], v[142:145], v[214:217], v[42:45]
	v_mfma_f32_16x16x32_bf16 v[30:33], v[130:133], v[218:221], v[30:33]
	v_mfma_f32_16x16x32_bf16 v[30:33], v[134:137], v[222:225], v[30:33]
	v_mfma_f32_16x16x32_bf16 v[26:29], v[138:141], v[218:221], v[26:29]
	v_mfma_f32_16x16x32_bf16 v[26:29], v[142:145], v[222:225], v[26:29]
	v_mfma_f32_16x16x32_bf16 v[14:17], v[130:133], v[226:229], v[14:17]
	v_mfma_f32_16x16x32_bf16 v[14:17], v[134:137], v[230:233], v[14:17]
	v_mfma_f32_16x16x32_bf16 v[10:13], v[138:141], v[226:229], v[10:13]
	v_mfma_f32_16x16x32_bf16 v[10:13], v[142:145], v[230:233], v[10:13]
	s_add_i32 vcc_hi, vcc_hi, 2
	s_add_u32 s76, s76, 0x100
	s_addc_u32 s77, s77, 0
	s_add_u32 s87, s87, 0x100
	s_addc_u32 vcc_lo, vcc_lo, 0
	v_mfma_f32_16x16x32_bf16 v[54:57], v[146:149], v[184:187], v[54:57]
	v_mfma_f32_16x16x32_bf16 v[54:57], v[150:153], v[188:191], v[54:57]
	v_mfma_f32_16x16x32_bf16 v[50:53], v[154:157], v[184:187], v[50:53]
	v_mfma_f32_16x16x32_bf16 v[50:53], v[158:161], v[188:191], v[50:53]
	v_mfma_f32_16x16x32_bf16 v[38:41], v[146:149], v[198:201], v[38:41]
	v_mfma_f32_16x16x32_bf16 v[38:41], v[150:153], v[214:217], v[38:41]
	v_mfma_f32_16x16x32_bf16 v[34:37], v[154:157], v[198:201], v[34:37]
	v_mfma_f32_16x16x32_bf16 v[34:37], v[158:161], v[214:217], v[34:37]
	v_mfma_f32_16x16x32_bf16 v[22:25], v[146:149], v[218:221], v[22:25]
	v_mfma_f32_16x16x32_bf16 v[22:25], v[150:153], v[222:225], v[22:25]
	v_mfma_f32_16x16x32_bf16 v[18:21], v[154:157], v[218:221], v[18:21]
	v_mfma_f32_16x16x32_bf16 v[18:21], v[158:161], v[222:225], v[18:21]
	v_mfma_f32_16x16x32_bf16 v[6:9], v[146:149], v[226:229], v[6:9]
	v_mfma_f32_16x16x32_bf16 v[6:9], v[150:153], v[230:233], v[6:9]
	v_mfma_f32_16x16x32_bf16 v[2:5], v[154:157], v[226:229], v[2:5]
	v_mfma_f32_16x16x32_bf16 v[2:5], v[158:161], v[230:233], v[2:5]
	s_barrier
	s_cmp_gt_u32 vcc_hi, 13
	s_cbranch_scc0 .LBB0_778
	s_setprio 0
	s_and_b64 vcc, exec, s[50:51]
	s_cbranch_vccz .LBB0_781
	s_barrier

.Lmid1_850:
	s_add_u32 s20, s56, 0xfffc0080
	s_addc_u32 s21, s57, -1
	s_cmp_eq_u32 s91, 12
	s_cselect_b32 s59, s76, s21
	s_cselect_b32 s58, s77, s20
	s_cselect_b32 s21, s69, s87
	s_cselect_b32 s20, s79, s86
	s_add_i32 m0, s15, 0xc000
	v_lshl_add_u64 v[142:143], s[56:57], 0, v[136:137]
	global_load_lds_dwordx4 v[142:143], off
	s_add_i32 m0, s15, 0xe000
	v_lshl_add_u64 v[142:143], v[142:143], 0, s[72:73]
	global_load_lds_dwordx4 v[142:143], off
	s_waitcnt vmcnt(8) lgkmcnt(0)
	s_barrier
	v_mfma_f32_16x16x32_bf16 v[126:129], v[138:141], v[198:201], 0
	v_mfma_f32_16x16x32_bf16 v[126:129], v[146:149], v[214:217], v[126:129]
	v_mfma_f32_16x16x32_bf16 v[122:125], v[150:153], v[198:201], 0
	v_mfma_f32_16x16x32_bf16 v[122:125], v[158:161], v[214:217], v[122:125]
	v_mfma_f32_16x16x32_bf16 v[110:113], v[138:141], v[218:221], 0
	v_mfma_f32_16x16x32_bf16 v[110:113], v[146:149], v[222:225], v[110:113]
	v_mfma_f32_16x16x32_bf16 v[106:109], v[150:153], v[218:221], 0
	v_mfma_f32_16x16x32_bf16 v[106:109], v[158:161], v[222:225], v[106:109]
	v_mfma_f32_16x16x32_bf16 v[94:97], v[138:141], v[226:229], 0
	v_mfma_f32_16x16x32_bf16 v[94:97], v[146:149], v[230:233], v[94:97]
	v_mfma_f32_16x16x32_bf16 v[90:93], v[150:153], v[226:229], 0
	v_mfma_f32_16x16x32_bf16 v[90:93], v[158:161], v[230:233], v[90:93]
	v_mfma_f32_16x16x32_bf16 v[78:81], v[138:141], v[234:237], 0
	v_mfma_f32_16x16x32_bf16 v[78:81], v[146:149], v[238:241], v[78:81]
	v_mfma_f32_16x16x32_bf16 v[74:77], v[150:153], v[234:237], 0
	v_mfma_f32_16x16x32_bf16 v[74:77], v[158:161], v[238:241], v[74:77]
	v_mfma_f32_16x16x32_bf16 v[118:121], v[182:185], v[198:201], 0
	v_mfma_f32_16x16x32_bf16 v[118:121], v[186:189], v[214:217], v[118:121]
	v_mfma_f32_16x16x32_bf16 v[114:117], v[190:193], v[198:201], 0
	v_mfma_f32_16x16x32_bf16 v[114:117], v[194:197], v[214:217], v[114:117]
	v_mfma_f32_16x16x32_bf16 v[102:105], v[182:185], v[218:221], 0
	v_mfma_f32_16x16x32_bf16 v[102:105], v[186:189], v[222:225], v[102:105]
	v_mfma_f32_16x16x32_bf16 v[98:101], v[190:193], v[218:221], 0
	v_mfma_f32_16x16x32_bf16 v[98:101], v[194:197], v[222:225], v[98:101]
	v_mfma_f32_16x16x32_bf16 v[86:89], v[182:185], v[226:229], 0
	v_mfma_f32_16x16x32_bf16 v[86:89], v[186:189], v[230:233], v[86:89]
	v_mfma_f32_16x16x32_bf16 v[82:85], v[190:193], v[226:229], 0
	v_mfma_f32_16x16x32_bf16 v[82:85], v[194:197], v[230:233], v[82:85]
	v_mfma_f32_16x16x32_bf16 v[70:73], v[182:185], v[234:237], 0
	v_mfma_f32_16x16x32_bf16 v[70:73], v[186:189], v[238:241], v[70:73]
	v_mfma_f32_16x16x32_bf16 v[66:69], v[190:193], v[234:237], 0
	v_mfma_f32_16x16x32_bf16 v[66:69], v[194:197], v[238:241], v[66:69]
	s_barrier
	ds_read_b128 v[198:201], v157 offset:16384
	ds_read_b128 v[214:217], v157 offset:17408
	ds_read_b128 v[218:221], v157 offset:18432
	ds_read_b128 v[222:225], v157 offset:19456
	ds_read_b128 v[226:229], v157 offset:20480
	ds_read_b128 v[230:233], v157 offset:21504
	ds_read_b128 v[234:237], v157 offset:22528
	ds_read_b128 v[238:241], v157 offset:23552
	s_add_i32 m0, s14, 0x10000
	v_lshl_add_u64 v[142:143], s[20:21], 0, v[130:131]
	global_load_lds_dwordx4 v[142:143], off
	s_add_i32 m0, s14, 0x12000
	v_lshl_add_u64 v[162:163], v[142:143], 0, s[72:73]
	global_load_lds_dwordx4 v[162:163], off
	s_add_i32 m0, s14, 0x14000
	v_lshl_add_u64 v[162:163], v[142:143], 0, s[28:29]
	global_load_lds_dwordx4 v[162:163], off
	s_add_i32 m0, s14, 0x16000
	v_lshl_add_u64 v[162:163], v[142:143], 0, s[82:83]
	global_load_lds_dwordx4 v[162:163], off
	v_lshl_add_u64 v[162:163], s[58:59], 0, v[132:133]
	s_mov_b32 m0, s15
	v_lshl_add_u64 v[202:203], v[162:163], 0, s[72:73]
	global_load_lds_dwordx4 v[162:163], off
	s_mov_b32 m0, s42
	s_nop 0
	global_load_lds_dwordx4 v[202:203], off
	s_waitcnt vmcnt(8) lgkmcnt(0)
	s_barrier
	v_mfma_f32_16x16x32_bf16 v[62:65], v[138:141], v[198:201], 0
	v_mfma_f32_16x16x32_bf16 v[62:65], v[146:149], v[214:217], v[62:65]
	v_mfma_f32_16x16x32_bf16 v[58:61], v[150:153], v[198:201], 0
	v_mfma_f32_16x16x32_bf16 v[58:61], v[158:161], v[214:217], v[58:61]
	v_mfma_f32_16x16x32_bf16 v[46:49], v[138:141], v[218:221], 0
	v_mfma_f32_16x16x32_bf16 v[46:49], v[146:149], v[222:225], v[46:49]
	v_mfma_f32_16x16x32_bf16 v[42:45], v[150:153], v[218:221], 0
	v_mfma_f32_16x16x32_bf16 v[42:45], v[158:161], v[222:225], v[42:45]
	v_mfma_f32_16x16x32_bf16 v[30:33], v[138:141], v[226:229], 0
	v_mfma_f32_16x16x32_bf16 v[30:33], v[146:149], v[230:233], v[30:33]
	v_mfma_f32_16x16x32_bf16 v[26:29], v[150:153], v[226:229], 0
	v_mfma_f32_16x16x32_bf16 v[26:29], v[158:161], v[230:233], v[26:29]
	v_mfma_f32_16x16x32_bf16 v[14:17], v[138:141], v[234:237], 0
	v_mfma_f32_16x16x32_bf16 v[14:17], v[146:149], v[238:241], v[14:17]
	v_mfma_f32_16x16x32_bf16 v[10:13], v[150:153], v[234:237], 0
	v_mfma_f32_16x16x32_bf16 v[10:13], v[158:161], v[238:241], v[10:13]
	v_mfma_f32_16x16x32_bf16 v[54:57], v[182:185], v[198:201], 0
	v_mfma_f32_16x16x32_bf16 v[54:57], v[186:189], v[214:217], v[54:57]
	v_mfma_f32_16x16x32_bf16 v[50:53], v[190:193], v[198:201], 0
	v_mfma_f32_16x16x32_bf16 v[50:53], v[194:197], v[214:217], v[50:53]
	v_mfma_f32_16x16x32_bf16 v[38:41], v[182:185], v[218:221], 0
	v_mfma_f32_16x16x32_bf16 v[38:41], v[186:189], v[222:225], v[38:41]
	v_mfma_f32_16x16x32_bf16 v[34:37], v[190:193], v[218:221], 0
	v_mfma_f32_16x16x32_bf16 v[34:37], v[194:197], v[222:225], v[34:37]
	v_mfma_f32_16x16x32_bf16 v[22:25], v[182:185], v[226:229], 0
	v_mfma_f32_16x16x32_bf16 v[22:25], v[186:189], v[230:233], v[22:25]
	v_mfma_f32_16x16x32_bf16 v[18:21], v[190:193], v[226:229], 0
	v_mfma_f32_16x16x32_bf16 v[18:21], v[194:197], v[230:233], v[18:21]
	v_mfma_f32_16x16x32_bf16 v[6:9], v[182:185], v[234:237], 0
	v_mfma_f32_16x16x32_bf16 v[6:9], v[186:189], v[238:241], v[6:9]
	v_mfma_f32_16x16x32_bf16 v[2:5], v[190:193], v[234:237], 0
	v_mfma_f32_16x16x32_bf16 v[2:5], v[194:197], v[238:241], v[2:5]
	s_barrier
	ds_read_b128 v[138:141], v243 offset:32768
	ds_read_b128 v[146:149], v243 offset:33792
	ds_read_b128 v[150:153], v243 offset:34816
	ds_read_b128 v[158:161], v243 offset:35840
	ds_read_b128 v[182:185], v243 offset:49152
	ds_read_b128 v[186:189], v243 offset:50176
	ds_read_b128 v[190:193], v243 offset:51200
	ds_read_b128 v[194:197], v243 offset:52224
	ds_read_b128 v[198:201], v157 offset:32768
	ds_read_b128 v[214:217], v157 offset:33792
	ds_read_b128 v[218:221], v157 offset:34816
	ds_read_b128 v[222:225], v157 offset:35840
	ds_read_b128 v[226:229], v157 offset:36864
	ds_read_b128 v[230:233], v157 offset:37888
	ds_read_b128 v[234:237], v157 offset:38912
	ds_read_b128 v[238:241], v157 offset:39936
	s_mov_b32 m0, s43
	v_lshl_add_u64 v[202:203], v[162:163], 0, s[28:29]
	global_load_lds_dwordx4 v[202:203], off
	v_lshl_add_u64 v[202:203], v[162:163], 0, s[82:83]
	s_mov_b32 m0, s46
	s_nop 0
	global_load_lds_dwordx4 v[202:203], off
	s_waitcnt vmcnt(8) lgkmcnt(0)
	s_barrier
	v_mfma_f32_16x16x32_bf16 v[126:129], v[138:141], v[198:201], v[126:129]
	v_mfma_f32_16x16x32_bf16 v[126:129], v[146:149], v[214:217], v[126:129]
	v_mfma_f32_16x16x32_bf16 v[122:125], v[150:153], v[198:201], v[122:125]
	v_mfma_f32_16x16x32_bf16 v[122:125], v[158:161], v[214:217], v[122:125]
	v_mfma_f32_16x16x32_bf16 v[110:113], v[138:141], v[218:221], v[110:113]
	v_mfma_f32_16x16x32_bf16 v[110:113], v[146:149], v[222:225], v[110:113]
	v_mfma_f32_16x16x32_bf16 v[106:109], v[150:153], v[218:221], v[106:109]
	v_mfma_f32_16x16x32_bf16 v[106:109], v[158:161], v[222:225], v[106:109]
	v_mfma_f32_16x16x32_bf16 v[94:97], v[138:141], v[226:229], v[94:97]
	v_mfma_f32_16x16x32_bf16 v[94:97], v[146:149], v[230:233], v[94:97]
	v_mfma_f32_16x16x32_bf16 v[90:93], v[150:153], v[226:229], v[90:93]
	v_mfma_f32_16x16x32_bf16 v[90:93], v[158:161], v[230:233], v[90:93]
	v_mfma_f32_16x16x32_bf16 v[78:81], v[138:141], v[234:237], v[78:81]
	v_mfma_f32_16x16x32_bf16 v[78:81], v[146:149], v[238:241], v[78:81]
	v_mfma_f32_16x16x32_bf16 v[74:77], v[150:153], v[234:237], v[74:77]
	v_mfma_f32_16x16x32_bf16 v[74:77], v[158:161], v[238:241], v[74:77]
	v_mfma_f32_16x16x32_bf16 v[118:121], v[182:185], v[198:201], v[118:121]
	v_mfma_f32_16x16x32_bf16 v[118:121], v[186:189], v[214:217], v[118:121]
	v_mfma_f32_16x16x32_bf16 v[114:117], v[190:193], v[198:201], v[114:117]
	v_mfma_f32_16x16x32_bf16 v[114:117], v[194:197], v[214:217], v[114:117]
	v_mfma_f32_16x16x32_bf16 v[102:105], v[182:185], v[218:221], v[102:105]
	v_mfma_f32_16x16x32_bf16 v[102:105], v[186:189], v[222:225], v[102:105]
	v_mfma_f32_16x16x32_bf16 v[98:101], v[190:193], v[218:221], v[98:101]
	v_mfma_f32_16x16x32_bf16 v[98:101], v[194:197], v[222:225], v[98:101]
	v_mfma_f32_16x16x32_bf16 v[86:89], v[182:185], v[226:229], v[86:89]
	v_mfma_f32_16x16x32_bf16 v[86:89], v[186:189], v[230:233], v[86:89]
	v_mfma_f32_16x16x32_bf16 v[82:85], v[190:193], v[226:229], v[82:85]
	v_mfma_f32_16x16x32_bf16 v[82:85], v[194:197], v[230:233], v[82:85]
	v_mfma_f32_16x16x32_bf16 v[70:73], v[182:185], v[234:237], v[70:73]
	v_mfma_f32_16x16x32_bf16 v[70:73], v[186:189], v[238:241], v[70:73]
	v_mfma_f32_16x16x32_bf16 v[66:69], v[190:193], v[234:237], v[66:69]
	v_mfma_f32_16x16x32_bf16 v[66:69], v[194:197], v[238:241], v[66:69]
	s_barrier
	ds_read_b128 v[198:201], v157 offset:49152
	ds_read_b128 v[214:217], v157 offset:50176
	ds_read_b128 v[218:221], v157 offset:51200
	ds_read_b128 v[222:225], v157 offset:52224
	ds_read_b128 v[226:229], v157 offset:53248
	ds_read_b128 v[230:233], v157 offset:54272
	ds_read_b128 v[234:237], v157 offset:55296
	ds_read_b128 v[238:241], v157 offset:56320
	s_add_i32 m0, s14, 0x18000
	v_lshl_add_u64 v[202:203], v[142:143], 0, s[34:35]
	global_load_lds_dwordx4 v[202:203], off
	s_add_i32 m0, s14, 0x1a000
	v_lshl_add_u64 v[202:203], v[142:143], 0, s[38:39]
	global_load_lds_dwordx4 v[202:203], off
	v_lshl_add_u64 v[202:203], v[142:143], 0, s[44:45]
	s_add_i32 m0, s14, 0x1c000
	v_lshl_add_u64 v[142:143], v[142:143], 0, s[10:11]
	global_load_lds_dwordx4 v[202:203], off
	s_add_i32 m0, s14, 0x1e000
	s_nop 0
	global_load_lds_dwordx4 v[142:143], off
	v_lshl_add_u64 v[142:143], v[162:163], 0, s[34:35]
	s_mov_b32 m0, s47
	s_nop 0
	global_load_lds_dwordx4 v[142:143], off
	v_lshl_add_u64 v[142:143], v[162:163], 0, s[38:39]
	s_mov_b32 m0, s96
	s_nop 0
	global_load_lds_dwordx4 v[142:143], off
	s_waitcnt vmcnt(8) lgkmcnt(0)
	s_barrier
	v_mfma_f32_16x16x32_bf16 v[62:65], v[138:141], v[198:201], v[62:65]
	v_mfma_f32_16x16x32_bf16 v[62:65], v[146:149], v[214:217], v[62:65]
	v_mfma_f32_16x16x32_bf16 v[58:61], v[150:153], v[198:201], v[58:61]
	v_mfma_f32_16x16x32_bf16 v[58:61], v[158:161], v[214:217], v[58:61]
	v_mfma_f32_16x16x32_bf16 v[46:49], v[138:141], v[218:221], v[46:49]
	v_mfma_f32_16x16x32_bf16 v[46:49], v[146:149], v[222:225], v[46:49]
	v_mfma_f32_16x16x32_bf16 v[42:45], v[150:153], v[218:221], v[42:45]
	v_mfma_f32_16x16x32_bf16 v[42:45], v[158:161], v[222:225], v[42:45]
	v_mfma_f32_16x16x32_bf16 v[30:33], v[138:141], v[226:229], v[30:33]
	v_mfma_f32_16x16x32_bf16 v[30:33], v[146:149], v[230:233], v[30:33]
	v_mfma_f32_16x16x32_bf16 v[26:29], v[150:153], v[226:229], v[26:29]
	v_mfma_f32_16x16x32_bf16 v[26:29], v[158:161], v[230:233], v[26:29]
	v_mfma_f32_16x16x32_bf16 v[14:17], v[138:141], v[234:237], v[14:17]
	v_mfma_f32_16x16x32_bf16 v[14:17], v[146:149], v[238:241], v[14:17]
	v_mfma_f32_16x16x32_bf16 v[10:13], v[150:153], v[234:237], v[10:13]
	v_mfma_f32_16x16x32_bf16 v[10:13], v[158:161], v[238:241], v[10:13]
	s_add_i32 s91, s91, 2
	s_add_u32 s56, s56, 0x100
	s_addc_u32 s57, s57, 0
	s_add_u32 s86, s86, 0x100
	s_addc_u32 s87, s87, 0
	v_mfma_f32_16x16x32_bf16 v[54:57], v[182:185], v[198:201], v[54:57]
	v_mfma_f32_16x16x32_bf16 v[54:57], v[186:189], v[214:217], v[54:57]
	v_mfma_f32_16x16x32_bf16 v[50:53], v[190:193], v[198:201], v[50:53]
	v_mfma_f32_16x16x32_bf16 v[50:53], v[194:197], v[214:217], v[50:53]
	v_mfma_f32_16x16x32_bf16 v[38:41], v[182:185], v[218:221], v[38:41]
	v_mfma_f32_16x16x32_bf16 v[38:41], v[186:189], v[222:225], v[38:41]
	v_mfma_f32_16x16x32_bf16 v[34:37], v[190:193], v[218:221], v[34:37]
	v_mfma_f32_16x16x32_bf16 v[34:37], v[194:197], v[222:225], v[34:37]
	v_mfma_f32_16x16x32_bf16 v[22:25], v[182:185], v[226:229], v[22:25]
	v_mfma_f32_16x16x32_bf16 v[22:25], v[186:189], v[230:233], v[22:25]
	v_mfma_f32_16x16x32_bf16 v[18:21], v[190:193], v[226:229], v[18:21]
	v_mfma_f32_16x16x32_bf16 v[18:21], v[194:197], v[230:233], v[18:21]
	v_mfma_f32_16x16x32_bf16 v[6:9], v[182:185], v[234:237], v[6:9]
	v_mfma_f32_16x16x32_bf16 v[6:9], v[186:189], v[238:241], v[6:9]
	v_mfma_f32_16x16x32_bf16 v[2:5], v[190:193], v[234:237], v[2:5]
	v_mfma_f32_16x16x32_bf16 v[2:5], v[194:197], v[238:241], v[2:5]
	s_barrier
	s_branch .LBB0_850
	.p2alignl 6, 3212836864
.LBB0_850:
	ds_read_b128 v[138:141], v243
	ds_read_b128 v[146:149], v243 offset:1024
	ds_read_b128 v[150:153], v243 offset:2048
	ds_read_b128 v[158:161], v243 offset:3072
	ds_read_b128 v[182:185], v243 offset:16384
	ds_read_b128 v[186:189], v243 offset:17408
	ds_read_b128 v[190:193], v243 offset:18432
	ds_read_b128 v[194:197], v243 offset:19456
	ds_read_b128 v[198:201], v157
	ds_read_b128 v[214:217], v157 offset:1024
	ds_read_b128 v[218:221], v157 offset:2048
	ds_read_b128 v[222:225], v157 offset:3072
	ds_read_b128 v[226:229], v157 offset:4096
	ds_read_b128 v[230:233], v157 offset:5120
	ds_read_b128 v[234:237], v157 offset:6144
	ds_read_b128 v[238:241], v157 offset:7168
	s_add_u32 s20, s56, 0xfffc0080
	s_addc_u32 s21, s57, -1
	s_cmp_eq_u32 s91, 12
	s_cselect_b32 s59, s76, s21
	s_cselect_b32 s58, s77, s20
	s_cselect_b32 s21, s69, s87
	s_cselect_b32 s20, s79, s86
	s_add_i32 m0, s15, 0xc000
	v_lshl_add_u64 v[142:143], s[56:57], 0, v[136:137]
	global_load_lds_dwordx4 v[142:143], off
	s_add_i32 m0, s15, 0xe000
	v_lshl_add_u64 v[142:143], v[142:143], 0, s[72:73]
	global_load_lds_dwordx4 v[142:143], off
	s_waitcnt vmcnt(8) lgkmcnt(0)
	s_barrier
	v_mfma_f32_16x16x32_bf16 v[126:129], v[138:141], v[198:201], v[126:129]
	v_mfma_f32_16x16x32_bf16 v[126:129], v[146:149], v[214:217], v[126:129]
	v_mfma_f32_16x16x32_bf16 v[122:125], v[150:153], v[198:201], v[122:125]
	v_mfma_f32_16x16x32_bf16 v[122:125], v[158:161], v[214:217], v[122:125]
	v_mfma_f32_16x16x32_bf16 v[110:113], v[138:141], v[218:221], v[110:113]
	v_mfma_f32_16x16x32_bf16 v[110:113], v[146:149], v[222:225], v[110:113]
	v_mfma_f32_16x16x32_bf16 v[106:109], v[150:153], v[218:221], v[106:109]
	v_mfma_f32_16x16x32_bf16 v[106:109], v[158:161], v[222:225], v[106:109]
	v_mfma_f32_16x16x32_bf16 v[94:97], v[138:141], v[226:229], v[94:97]
	v_mfma_f32_16x16x32_bf16 v[94:97], v[146:149], v[230:233], v[94:97]
	v_mfma_f32_16x16x32_bf16 v[90:93], v[150:153], v[226:229], v[90:93]
	v_mfma_f32_16x16x32_bf16 v[90:93], v[158:161], v[230:233], v[90:93]
	v_mfma_f32_16x16x32_bf16 v[78:81], v[138:141], v[234:237], v[78:81]
	v_mfma_f32_16x16x32_bf16 v[78:81], v[146:149], v[238:241], v[78:81]
	v_mfma_f32_16x16x32_bf16 v[74:77], v[150:153], v[234:237], v[74:77]
	v_mfma_f32_16x16x32_bf16 v[74:77], v[158:161], v[238:241], v[74:77]
	v_mfma_f32_16x16x32_bf16 v[118:121], v[182:185], v[198:201], v[118:121]
	v_mfma_f32_16x16x32_bf16 v[118:121], v[186:189], v[214:217], v[118:121]
	v_mfma_f32_16x16x32_bf16 v[114:117], v[190:193], v[198:201], v[114:117]
	v_mfma_f32_16x16x32_bf16 v[114:117], v[194:197], v[214:217], v[114:117]
	v_mfma_f32_16x16x32_bf16 v[102:105], v[182:185], v[218:221], v[102:105]
	v_mfma_f32_16x16x32_bf16 v[102:105], v[186:189], v[222:225], v[102:105]
	v_mfma_f32_16x16x32_bf16 v[98:101], v[190:193], v[218:221], v[98:101]
	v_mfma_f32_16x16x32_bf16 v[98:101], v[194:197], v[222:225], v[98:101]
	v_mfma_f32_16x16x32_bf16 v[86:89], v[182:185], v[226:229], v[86:89]
	v_mfma_f32_16x16x32_bf16 v[86:89], v[186:189], v[230:233], v[86:89]
	v_mfma_f32_16x16x32_bf16 v[82:85], v[190:193], v[226:229], v[82:85]
	v_mfma_f32_16x16x32_bf16 v[82:85], v[194:197], v[230:233], v[82:85]
	v_mfma_f32_16x16x32_bf16 v[70:73], v[182:185], v[234:237], v[70:73]
	v_mfma_f32_16x16x32_bf16 v[70:73], v[186:189], v[238:241], v[70:73]
	v_mfma_f32_16x16x32_bf16 v[66:69], v[190:193], v[234:237], v[66:69]
	v_mfma_f32_16x16x32_bf16 v[66:69], v[194:197], v[238:241], v[66:69]
	s_barrier
	ds_read_b128 v[198:201], v157 offset:16384
	ds_read_b128 v[214:217], v157 offset:17408
	ds_read_b128 v[218:221], v157 offset:18432
	ds_read_b128 v[222:225], v157 offset:19456
	ds_read_b128 v[226:229], v157 offset:20480
	ds_read_b128 v[230:233], v157 offset:21504
	ds_read_b128 v[234:237], v157 offset:22528
	ds_read_b128 v[238:241], v157 offset:23552
	s_add_i32 m0, s14, 0x10000
	v_lshl_add_u64 v[142:143], s[20:21], 0, v[130:131]
	global_load_lds_dwordx4 v[142:143], off
	s_add_i32 m0, s14, 0x12000
	v_lshl_add_u64 v[162:163], v[142:143], 0, s[72:73]
	global_load_lds_dwordx4 v[162:163], off
	s_add_i32 m0, s14, 0x14000
	v_lshl_add_u64 v[162:163], v[142:143], 0, s[28:29]
	global_load_lds_dwordx4 v[162:163], off
	s_add_i32 m0, s14, 0x16000
	v_lshl_add_u64 v[162:163], v[142:143], 0, s[82:83]
	global_load_lds_dwordx4 v[162:163], off
	v_lshl_add_u64 v[162:163], s[58:59], 0, v[132:133]
	s_mov_b32 m0, s15
	v_lshl_add_u64 v[202:203], v[162:163], 0, s[72:73]
	global_load_lds_dwordx4 v[162:163], off
	s_mov_b32 m0, s42
	s_nop 0
	global_load_lds_dwordx4 v[202:203], off
	s_waitcnt vmcnt(8) lgkmcnt(0)
	s_barrier
	v_mfma_f32_16x16x32_bf16 v[62:65], v[138:141], v[198:201], v[62:65]
	v_mfma_f32_16x16x32_bf16 v[62:65], v[146:149], v[214:217], v[62:65]
	v_mfma_f32_16x16x32_bf16 v[58:61], v[150:153], v[198:201], v[58:61]
	v_mfma_f32_16x16x32_bf16 v[58:61], v[158:161], v[214:217], v[58:61]
	v_mfma_f32_16x16x32_bf16 v[46:49], v[138:141], v[218:221], v[46:49]
	v_mfma_f32_16x16x32_bf16 v[46:49], v[146:149], v[222:225], v[46:49]
	v_mfma_f32_16x16x32_bf16 v[42:45], v[150:153], v[218:221], v[42:45]
	v_mfma_f32_16x16x32_bf16 v[42:45], v[158:161], v[222:225], v[42:45]
	v_mfma_f32_16x16x32_bf16 v[30:33], v[138:141], v[226:229], v[30:33]
	v_mfma_f32_16x16x32_bf16 v[30:33], v[146:149], v[230:233], v[30:33]
	v_mfma_f32_16x16x32_bf16 v[26:29], v[150:153], v[226:229], v[26:29]
	v_mfma_f32_16x16x32_bf16 v[26:29], v[158:161], v[230:233], v[26:29]
	v_mfma_f32_16x16x32_bf16 v[14:17], v[138:141], v[234:237], v[14:17]
	v_mfma_f32_16x16x32_bf16 v[14:17], v[146:149], v[238:241], v[14:17]
	v_mfma_f32_16x16x32_bf16 v[10:13], v[150:153], v[234:237], v[10:13]
	v_mfma_f32_16x16x32_bf16 v[10:13], v[158:161], v[238:241], v[10:13]
	v_mfma_f32_16x16x32_bf16 v[54:57], v[182:185], v[198:201], v[54:57]
	v_mfma_f32_16x16x32_bf16 v[54:57], v[186:189], v[214:217], v[54:57]
	v_mfma_f32_16x16x32_bf16 v[50:53], v[190:193], v[198:201], v[50:53]
	v_mfma_f32_16x16x32_bf16 v[50:53], v[194:197], v[214:217], v[50:53]
	v_mfma_f32_16x16x32_bf16 v[38:41], v[182:185], v[218:221], v[38:41]
	v_mfma_f32_16x16x32_bf16 v[38:41], v[186:189], v[222:225], v[38:41]
	v_mfma_f32_16x16x32_bf16 v[34:37], v[190:193], v[218:221], v[34:37]
	v_mfma_f32_16x16x32_bf16 v[34:37], v[194:197], v[222:225], v[34:37]
	v_mfma_f32_16x16x32_bf16 v[22:25], v[182:185], v[226:229], v[22:25]
	v_mfma_f32_16x16x32_bf16 v[22:25], v[186:189], v[230:233], v[22:25]
	v_mfma_f32_16x16x32_bf16 v[18:21], v[190:193], v[226:229], v[18:21]
	v_mfma_f32_16x16x32_bf16 v[18:21], v[194:197], v[230:233], v[18:21]
	v_mfma_f32_16x16x32_bf16 v[6:9], v[182:185], v[234:237], v[6:9]
	v_mfma_f32_16x16x32_bf16 v[6:9], v[186:189], v[238:241], v[6:9]
	v_mfma_f32_16x16x32_bf16 v[2:5], v[190:193], v[234:237], v[2:5]
	v_mfma_f32_16x16x32_bf16 v[2:5], v[194:197], v[238:241], v[2:5]
	s_barrier
	ds_read_b128 v[138:141], v243 offset:32768
	ds_read_b128 v[146:149], v243 offset:33792
	ds_read_b128 v[150:153], v243 offset:34816
	ds_read_b128 v[158:161], v243 offset:35840
	ds_read_b128 v[182:185], v243 offset:49152
	ds_read_b128 v[186:189], v243 offset:50176
	ds_read_b128 v[190:193], v243 offset:51200
	ds_read_b128 v[194:197], v243 offset:52224
	ds_read_b128 v[198:201], v157 offset:32768
	ds_read_b128 v[214:217], v157 offset:33792
	ds_read_b128 v[218:221], v157 offset:34816
	ds_read_b128 v[222:225], v157 offset:35840
	ds_read_b128 v[226:229], v157 offset:36864
	ds_read_b128 v[230:233], v157 offset:37888
	ds_read_b128 v[234:237], v157 offset:38912
	ds_read_b128 v[238:241], v157 offset:39936
	s_mov_b32 m0, s43
	v_lshl_add_u64 v[202:203], v[162:163], 0, s[28:29]
	global_load_lds_dwordx4 v[202:203], off
	v_lshl_add_u64 v[202:203], v[162:163], 0, s[82:83]
	s_mov_b32 m0, s46
	s_nop 0
	global_load_lds_dwordx4 v[202:203], off
	s_waitcnt vmcnt(8) lgkmcnt(0)
	s_barrier
	v_mfma_f32_16x16x32_bf16 v[126:129], v[138:141], v[198:201], v[126:129]
	v_mfma_f32_16x16x32_bf16 v[126:129], v[146:149], v[214:217], v[126:129]
	v_mfma_f32_16x16x32_bf16 v[122:125], v[150:153], v[198:201], v[122:125]
	v_mfma_f32_16x16x32_bf16 v[122:125], v[158:161], v[214:217], v[122:125]
	v_mfma_f32_16x16x32_bf16 v[110:113], v[138:141], v[218:221], v[110:113]
	v_mfma_f32_16x16x32_bf16 v[110:113], v[146:149], v[222:225], v[110:113]
	v_mfma_f32_16x16x32_bf16 v[106:109], v[150:153], v[218:221], v[106:109]
	v_mfma_f32_16x16x32_bf16 v[106:109], v[158:161], v[222:225], v[106:109]
	v_mfma_f32_16x16x32_bf16 v[94:97], v[138:141], v[226:229], v[94:97]
	v_mfma_f32_16x16x32_bf16 v[94:97], v[146:149], v[230:233], v[94:97]
	v_mfma_f32_16x16x32_bf16 v[90:93], v[150:153], v[226:229], v[90:93]
	v_mfma_f32_16x16x32_bf16 v[90:93], v[158:161], v[230:233], v[90:93]
	v_mfma_f32_16x16x32_bf16 v[78:81], v[138:141], v[234:237], v[78:81]
	v_mfma_f32_16x16x32_bf16 v[78:81], v[146:149], v[238:241], v[78:81]
	v_mfma_f32_16x16x32_bf16 v[74:77], v[150:153], v[234:237], v[74:77]
	v_mfma_f32_16x16x32_bf16 v[74:77], v[158:161], v[238:241], v[74:77]
	v_mfma_f32_16x16x32_bf16 v[118:121], v[182:185], v[198:201], v[118:121]
	v_mfma_f32_16x16x32_bf16 v[118:121], v[186:189], v[214:217], v[118:121]
	v_mfma_f32_16x16x32_bf16 v[114:117], v[190:193], v[198:201], v[114:117]
	v_mfma_f32_16x16x32_bf16 v[114:117], v[194:197], v[214:217], v[114:117]
	v_mfma_f32_16x16x32_bf16 v[102:105], v[182:185], v[218:221], v[102:105]
	v_mfma_f32_16x16x32_bf16 v[102:105], v[186:189], v[222:225], v[102:105]
	v_mfma_f32_16x16x32_bf16 v[98:101], v[190:193], v[218:221], v[98:101]
	v_mfma_f32_16x16x32_bf16 v[98:101], v[194:197], v[222:225], v[98:101]
	v_mfma_f32_16x16x32_bf16 v[86:89], v[182:185], v[226:229], v[86:89]
	v_mfma_f32_16x16x32_bf16 v[86:89], v[186:189], v[230:233], v[86:89]
	v_mfma_f32_16x16x32_bf16 v[82:85], v[190:193], v[226:229], v[82:85]
	v_mfma_f32_16x16x32_bf16 v[82:85], v[194:197], v[230:233], v[82:85]
	v_mfma_f32_16x16x32_bf16 v[70:73], v[182:185], v[234:237], v[70:73]
	v_mfma_f32_16x16x32_bf16 v[70:73], v[186:189], v[238:241], v[70:73]
	v_mfma_f32_16x16x32_bf16 v[66:69], v[190:193], v[234:237], v[66:69]
	v_mfma_f32_16x16x32_bf16 v[66:69], v[194:197], v[238:241], v[66:69]
	s_barrier
	ds_read_b128 v[198:201], v157 offset:49152
	ds_read_b128 v[214:217], v157 offset:50176
	ds_read_b128 v[218:221], v157 offset:51200
	ds_read_b128 v[222:225], v157 offset:52224
	ds_read_b128 v[226:229], v157 offset:53248
	ds_read_b128 v[230:233], v157 offset:54272
	ds_read_b128 v[234:237], v157 offset:55296
	ds_read_b128 v[238:241], v157 offset:56320
	s_add_i32 m0, s14, 0x18000
	v_lshl_add_u64 v[202:203], v[142:143], 0, s[34:35]
	global_load_lds_dwordx4 v[202:203], off
	s_add_i32 m0, s14, 0x1a000
	v_lshl_add_u64 v[202:203], v[142:143], 0, s[38:39]
	global_load_lds_dwordx4 v[202:203], off
	v_lshl_add_u64 v[202:203], v[142:143], 0, s[44:45]
	s_add_i32 m0, s14, 0x1c000
	v_lshl_add_u64 v[142:143], v[142:143], 0, s[10:11]
	global_load_lds_dwordx4 v[202:203], off
	s_add_i32 m0, s14, 0x1e000
	s_nop 0
	global_load_lds_dwordx4 v[142:143], off
	v_lshl_add_u64 v[142:143], v[162:163], 0, s[34:35]
	s_mov_b32 m0, s47
	s_nop 0
	global_load_lds_dwordx4 v[142:143], off
	v_lshl_add_u64 v[142:143], v[162:163], 0, s[38:39]
	s_mov_b32 m0, s96
	s_nop 0
	global_load_lds_dwordx4 v[142:143], off
	s_waitcnt vmcnt(8) lgkmcnt(0)
	s_barrier
	v_mfma_f32_16x16x32_bf16 v[62:65], v[138:141], v[198:201], v[62:65]
	v_mfma_f32_16x16x32_bf16 v[62:65], v[146:149], v[214:217], v[62:65]
	v_mfma_f32_16x16x32_bf16 v[58:61], v[150:153], v[198:201], v[58:61]
	v_mfma_f32_16x16x32_bf16 v[58:61], v[158:161], v[214:217], v[58:61]
	v_mfma_f32_16x16x32_bf16 v[46:49], v[138:141], v[218:221], v[46:49]
	v_mfma_f32_16x16x32_bf16 v[46:49], v[146:149], v[222:225], v[46:49]
	v_mfma_f32_16x16x32_bf16 v[42:45], v[150:153], v[218:221], v[42:45]
	v_mfma_f32_16x16x32_bf16 v[42:45], v[158:161], v[222:225], v[42:45]
	v_mfma_f32_16x16x32_bf16 v[30:33], v[138:141], v[226:229], v[30:33]
	v_mfma_f32_16x16x32_bf16 v[30:33], v[146:149], v[230:233], v[30:33]
	v_mfma_f32_16x16x32_bf16 v[26:29], v[150:153], v[226:229], v[26:29]
	v_mfma_f32_16x16x32_bf16 v[26:29], v[158:161], v[230:233], v[26:29]
	v_mfma_f32_16x16x32_bf16 v[14:17], v[138:141], v[234:237], v[14:17]
	v_mfma_f32_16x16x32_bf16 v[14:17], v[146:149], v[238:241], v[14:17]
	v_mfma_f32_16x16x32_bf16 v[10:13], v[150:153], v[234:237], v[10:13]
	v_mfma_f32_16x16x32_bf16 v[10:13], v[158:161], v[238:241], v[10:13]
	s_add_i32 s91, s91, 2
	s_add_u32 s56, s56, 0x100
	s_addc_u32 s57, s57, 0
	s_add_u32 s86, s86, 0x100
	s_addc_u32 s87, s87, 0
	v_mfma_f32_16x16x32_bf16 v[54:57], v[182:185], v[198:201], v[54:57]
	v_mfma_f32_16x16x32_bf16 v[54:57], v[186:189], v[214:217], v[54:57]
	v_mfma_f32_16x16x32_bf16 v[50:53], v[190:193], v[198:201], v[50:53]
	v_mfma_f32_16x16x32_bf16 v[50:53], v[194:197], v[214:217], v[50:53]
	v_mfma_f32_16x16x32_bf16 v[38:41], v[182:185], v[218:221], v[38:41]
	v_mfma_f32_16x16x32_bf16 v[38:41], v[186:189], v[222:225], v[38:41]
	v_mfma_f32_16x16x32_bf16 v[34:37], v[190:193], v[218:221], v[34:37]
	v_mfma_f32_16x16x32_bf16 v[34:37], v[194:197], v[222:225], v[34:37]
	v_mfma_f32_16x16x32_bf16 v[22:25], v[182:185], v[226:229], v[22:25]
	v_mfma_f32_16x16x32_bf16 v[22:25], v[186:189], v[230:233], v[22:25]
	v_mfma_f32_16x16x32_bf16 v[18:21], v[190:193], v[226:229], v[18:21]
	v_mfma_f32_16x16x32_bf16 v[18:21], v[194:197], v[230:233], v[18:21]
	v_mfma_f32_16x16x32_bf16 v[6:9], v[182:185], v[234:237], v[6:9]
	v_mfma_f32_16x16x32_bf16 v[6:9], v[186:189], v[238:241], v[6:9]
	v_mfma_f32_16x16x32_bf16 v[2:5], v[190:193], v[234:237], v[2:5]
	v_mfma_f32_16x16x32_bf16 v[2:5], v[194:197], v[238:241], v[2:5]
	s_barrier
	s_cmp_gt_u32 s91, 13
	s_cbranch_scc0 .LBB0_850
	s_setprio 0
	s_and_b64 vcc, exec, s[62:63]
	s_cbranch_vccz .LBB0_853
	s_barrier
